# GEMM f32 epilogue modes 5/6 (G_L2 outputs): one straight-line path per mode, bias loaded once, whole-line stores via the same DPP exchange
# baseline (speedup 1.0000x reference)
; __device__ __forceinline__ unsigned char* WSP() { return (unsigned char*)IN(41); }
; __device__ __forceinline__ void epilogue(const f32x4 (&acc)[2][2][4][2], const Unit& u, LAS unsigned char* lds, int wr, int wc, int fr, int fq) {
;     ...
;     int row0 = u.pm * BM + wr * 64 + fr; const int col0 = u.pn * BM + wc * 32 + 4 * fq;
;     if (u.part >= 0) { Cp = (const char*)(WSP() + WS_PB) + (size_t)u.part * 256 * D * 4; row0 = wr * 64 + fr; ldc = D; mode = 0; }
;     if (mode == 0 || mode >= 5) {
;         float* C = (float*)Cp; const float* bias = (const float*)rfl_ptr(jobs[u.j].bias);
; #pragma unroll
;         for (int ai = 0; ai < 2; ++ai)
; #pragma unroll
;             for (int m = 0; m < 4; ++m) { float* rowp = C + (size_t)(row0 + ai * HALF + m * 16) * ldc + col0;
; #pragma unroll
;                 for (int bj = 0; bj < 2; ++bj)
; #pragma unroll
;                     for (int n = 0; n < 2; ++n) { f32x4 v = acc[ai][bj][m][n];
;                         if (mode >= 5) { v += *(const f32x4*)(bias + col0 + bj * HALF + n * 16);
; #pragma unroll
;                             for (int q = 0; q < 4; ++q) { const float sg = __builtin_amdgcn_rcpf(1.f + __expf(-v[q])); v[q] = mode == 5 ? __expf(-0.6065306597126334f * sg) : sg; } }
;                         *(f32x4*)(rowp + bj * HALF + n * 16) = v; }
.Lepi_f56:
	s_lshl_b64 s[100:101], s[26:27], 5
	s_lshl_b64 s[2:3], s[26:27], 6
	v_mov_b32_e32 v250, s100
	v_mov_b32_e32 v251, s101
	v_sub_co_u32_e32 v250, vcc, 64, v250
	s_nop 1
	v_subb_co_u32_e32 v251, vcc, 0, v251, vcc
	v_mbcnt_lo_u32_b32 v248, -1, 0
	v_mbcnt_hi_u32_b32 v248, -1, v248
	v_and_b32_e32 v248, 8, v248
	v_cmp_ne_u32_e32 vcc, 0, v248
	s_nop 1
	v_cndmask_b32_e32 v250, 0, v250, vcc
	v_cndmask_b32_e32 v251, 0, v251, vcc
	v_lshl_add_u64 v[144:145], v[144:145], 0, v[250:251]
	v_lshl_add_u64 v[142:143], v[144:145], 0, s[100:101]
	s_nop 0
	global_load_dwordx4 v[236:239], v[140:141], off
	global_load_dwordx4 v[240:243], v[140:141], off offset:64
	global_load_dwordx4 v[244:247], v[140:141], off offset:512
	global_load_dwordx4 v[248:251], v[140:141], off offset:576
	s_and_b64 vcc, exec, s[8:9]
	s_waitcnt vmcnt(0)
	s_cbranch_vccnz .Lepi_f5
	v_pk_add_f32 v[130:131], v[130:131], v[238:239]
	v_pk_add_f32 v[128:129], v[128:129], v[236:237]
	v_mul_f32_e32 v130, 0xbfb8aa3b, v130
	v_mul_f32_e32 v128, 0xbfb8aa3b, v128
	v_mul_f32_e32 v129, 0xbfb8aa3b, v129
	v_mul_f32_e32 v131, 0xbfb8aa3b, v131
	v_exp_f32_e32 v128, v128
	v_exp_f32_e32 v129, v129
	v_exp_f32_e32 v130, v130
	v_exp_f32_e32 v131, v131
	v_add_f32_e32 v128, 1.0, v128
	v_add_f32_e32 v129, 1.0, v129
	v_add_f32_e32 v130, 1.0, v130
	v_add_f32_e32 v131, 1.0, v131
	v_rcp_f32_e32 v128, v128
	v_rcp_f32_e32 v129, v129
	v_rcp_f32_e32 v130, v130
	v_rcp_f32_e32 v131, v131
	v_pk_add_f32 v[126:127], v[126:127], v[242:243]
	v_pk_add_f32 v[124:125], v[124:125], v[240:241]
	v_mul_f32_e32 v126, 0xbfb8aa3b, v126
	v_mul_f32_e32 v124, 0xbfb8aa3b, v124
	v_mul_f32_e32 v125, 0xbfb8aa3b, v125
	v_mul_f32_e32 v127, 0xbfb8aa3b, v127
	v_exp_f32_e32 v124, v124
	v_exp_f32_e32 v125, v125
	v_exp_f32_e32 v126, v126
	v_exp_f32_e32 v127, v127
	v_add_f32_e32 v124, 1.0, v124
	v_add_f32_e32 v125, 1.0, v125
	v_add_f32_e32 v126, 1.0, v126
	v_add_f32_e32 v127, 1.0, v127
	v_rcp_f32_e32 v124, v124
	v_rcp_f32_e32 v125, v125
	v_rcp_f32_e32 v126, v126
	v_rcp_f32_e32 v127, v127
	s_nop 0
	v_mov_b32_dpp v252, v124 row_ror:8 row_mask:0xf bank_mask:0xf
	v_mov_b32_dpp v253, v125 row_ror:8 row_mask:0xf bank_mask:0xf
	v_mov_b32_dpp v254, v126 row_ror:8 row_mask:0xf bank_mask:0xf
	v_mov_b32_dpp v255, v127 row_ror:8 row_mask:0xf bank_mask:0xf
	v_mov_b32_dpp v124, v128 row_ror:8 row_mask:0xf bank_mask:0x3
	v_mov_b32_dpp v125, v129 row_ror:8 row_mask:0xf bank_mask:0x3
	v_mov_b32_dpp v126, v130 row_ror:8 row_mask:0xf bank_mask:0x3
	v_mov_b32_dpp v127, v131 row_ror:8 row_mask:0xf bank_mask:0x3
	v_mov_b32_dpp v128, v252 quad_perm:[0,1,2,3] row_mask:0xf bank_mask:0xc
	v_mov_b32_dpp v129, v253 quad_perm:[0,1,2,3] row_mask:0xf bank_mask:0xc
	v_mov_b32_dpp v130, v254 quad_perm:[0,1,2,3] row_mask:0xf bank_mask:0xc
	v_mov_b32_dpp v131, v255 quad_perm:[0,1,2,3] row_mask:0xf bank_mask:0xc
	global_store_dwordx4 v[144:145], v[128:131], off
	global_store_dwordx4 v[142:143], v[124:127], off
	v_pk_add_f32 v[122:123], v[122:123], v[246:247]
	v_pk_add_f32 v[120:121], v[120:121], v[244:245]
	v_mul_f32_e32 v122, 0xbfb8aa3b, v122
	v_mul_f32_e32 v120, 0xbfb8aa3b, v120
	v_mul_f32_e32 v121, 0xbfb8aa3b, v121
	v_mul_f32_e32 v123, 0xbfb8aa3b, v123
	v_exp_f32_e32 v120, v120
	v_exp_f32_e32 v121, v121
	v_exp_f32_e32 v122, v122
	v_exp_f32_e32 v123, v123
	v_add_f32_e32 v120, 1.0, v120
	v_add_f32_e32 v121, 1.0, v121
	v_add_f32_e32 v122, 1.0, v122
	v_add_f32_e32 v123, 1.0, v123
	v_rcp_f32_e32 v120, v120
	v_rcp_f32_e32 v121, v121
	v_rcp_f32_e32 v122, v122
	v_rcp_f32_e32 v123, v123
	v_pk_add_f32 v[118:119], v[118:119], v[250:251]
	v_pk_add_f32 v[116:117], v[116:117], v[248:249]
	v_mul_f32_e32 v118, 0xbfb8aa3b, v118
	v_mul_f32_e32 v116, 0xbfb8aa3b, v116
	v_mul_f32_e32 v117, 0xbfb8aa3b, v117
	v_mul_f32_e32 v119, 0xbfb8aa3b, v119
	v_exp_f32_e32 v116, v116
	v_exp_f32_e32 v117, v117
	v_exp_f32_e32 v118, v118
	v_exp_f32_e32 v119, v119
	v_add_f32_e32 v116, 1.0, v116
	v_add_f32_e32 v117, 1.0, v117
	v_add_f32_e32 v118, 1.0, v118
	v_add_f32_e32 v119, 1.0, v119
	v_rcp_f32_e32 v116, v116
	v_rcp_f32_e32 v117, v117
	v_rcp_f32_e32 v118, v118
	v_rcp_f32_e32 v119, v119
	s_nop 0
	v_mov_b32_dpp v252, v116 row_ror:8 row_mask:0xf bank_mask:0xf
	v_mov_b32_dpp v253, v117 row_ror:8 row_mask:0xf bank_mask:0xf
	v_mov_b32_dpp v254, v118 row_ror:8 row_mask:0xf bank_mask:0xf
	v_mov_b32_dpp v255, v119 row_ror:8 row_mask:0xf bank_mask:0xf
	v_mov_b32_dpp v116, v120 row_ror:8 row_mask:0xf bank_mask:0x3
	v_mov_b32_dpp v117, v121 row_ror:8 row_mask:0xf bank_mask:0x3
	v_mov_b32_dpp v118, v122 row_ror:8 row_mask:0xf bank_mask:0x3
	v_mov_b32_dpp v119, v123 row_ror:8 row_mask:0xf bank_mask:0x3
	v_mov_b32_dpp v120, v252 quad_perm:[0,1,2,3] row_mask:0xf bank_mask:0xc
	v_mov_b32_dpp v121, v253 quad_perm:[0,1,2,3] row_mask:0xf bank_mask:0xc
	v_mov_b32_dpp v122, v254 quad_perm:[0,1,2,3] row_mask:0xf bank_mask:0xc
	v_mov_b32_dpp v123, v255 quad_perm:[0,1,2,3] row_mask:0xf bank_mask:0xc
	global_store_dwordx4 v[144:145], v[120:123], off offset:512
	global_store_dwordx4 v[142:143], v[116:119], off offset:512
	v_lshl_add_u64 v[144:145], s[2:3], 0, v[144:145]
	v_lshl_add_u64 v[142:143], s[2:3], 0, v[142:143]
	v_pk_add_f32 v[114:115], v[114:115], v[238:239]
	v_pk_add_f32 v[112:113], v[112:113], v[236:237]
	v_mul_f32_e32 v114, 0xbfb8aa3b, v114
	v_mul_f32_e32 v112, 0xbfb8aa3b, v112
	v_mul_f32_e32 v113, 0xbfb8aa3b, v113
	v_mul_f32_e32 v115, 0xbfb8aa3b, v115
	v_exp_f32_e32 v112, v112
	v_exp_f32_e32 v113, v113
	v_exp_f32_e32 v114, v114
	v_exp_f32_e32 v115, v115
	v_add_f32_e32 v112, 1.0, v112
	v_add_f32_e32 v113, 1.0, v113
	v_add_f32_e32 v114, 1.0, v114
	v_add_f32_e32 v115, 1.0, v115
	v_rcp_f32_e32 v112, v112
	v_rcp_f32_e32 v113, v113
; __device__ __forceinline__ void epilogue(const f32x4 (&acc)[2][2][4][2], const Unit& u, LAS unsigned char* lds, int wr, int wc, int fr, int fq) {
;     ...
;                     for (int n = 0; n < 2; ++n) { f32x4 v = acc[ai][bj][m][n];
;                         if (mode >= 5) { v += *(const f32x4*)(bias + col0 + bj * HALF + n * 16);
; #pragma unroll
;                             for (int q = 0; q < 4; ++q) { const float sg = __builtin_amdgcn_rcpf(1.f + __expf(-v[q])); v[q] = mode == 5 ? __expf(-0.6065306597126334f * sg) : sg; } }
;                         *(f32x4*)(rowp + bj * HALF + n * 16) = v; }
	v_rcp_f32_e32 v114, v114
	v_rcp_f32_e32 v115, v115
	v_pk_add_f32 v[110:111], v[110:111], v[242:243]
	v_pk_add_f32 v[108:109], v[108:109], v[240:241]
	v_mul_f32_e32 v110, 0xbfb8aa3b, v110
	v_mul_f32_e32 v108, 0xbfb8aa3b, v108
	v_mul_f32_e32 v109, 0xbfb8aa3b, v109
	v_mul_f32_e32 v111, 0xbfb8aa3b, v111
	v_exp_f32_e32 v108, v108
	v_exp_f32_e32 v109, v109
	v_exp_f32_e32 v110, v110
	v_exp_f32_e32 v111, v111
	v_add_f32_e32 v108, 1.0, v108
	v_add_f32_e32 v109, 1.0, v109
	v_add_f32_e32 v110, 1.0, v110
	v_add_f32_e32 v111, 1.0, v111
	v_rcp_f32_e32 v108, v108
	v_rcp_f32_e32 v109, v109
	v_rcp_f32_e32 v110, v110
	v_rcp_f32_e32 v111, v111
	s_nop 0
	v_mov_b32_dpp v252, v108 row_ror:8 row_mask:0xf bank_mask:0xf
	v_mov_b32_dpp v253, v109 row_ror:8 row_mask:0xf bank_mask:0xf
	v_mov_b32_dpp v254, v110 row_ror:8 row_mask:0xf bank_mask:0xf
	v_mov_b32_dpp v255, v111 row_ror:8 row_mask:0xf bank_mask:0xf
	v_mov_b32_dpp v108, v112 row_ror:8 row_mask:0xf bank_mask:0x3
	v_mov_b32_dpp v109, v113 row_ror:8 row_mask:0xf bank_mask:0x3
	v_mov_b32_dpp v110, v114 row_ror:8 row_mask:0xf bank_mask:0x3
	v_mov_b32_dpp v111, v115 row_ror:8 row_mask:0xf bank_mask:0x3
	v_mov_b32_dpp v112, v252 quad_perm:[0,1,2,3] row_mask:0xf bank_mask:0xc
	v_mov_b32_dpp v113, v253 quad_perm:[0,1,2,3] row_mask:0xf bank_mask:0xc
	v_mov_b32_dpp v114, v254 quad_perm:[0,1,2,3] row_mask:0xf bank_mask:0xc
	v_mov_b32_dpp v115, v255 quad_perm:[0,1,2,3] row_mask:0xf bank_mask:0xc
	global_store_dwordx4 v[144:145], v[112:115], off
	global_store_dwordx4 v[142:143], v[108:111], off
	v_pk_add_f32 v[106:107], v[106:107], v[246:247]
	v_pk_add_f32 v[104:105], v[104:105], v[244:245]
	v_mul_f32_e32 v106, 0xbfb8aa3b, v106
	v_mul_f32_e32 v104, 0xbfb8aa3b, v104
	v_mul_f32_e32 v105, 0xbfb8aa3b, v105
	v_mul_f32_e32 v107, 0xbfb8aa3b, v107
	v_exp_f32_e32 v104, v104
	v_exp_f32_e32 v105, v105
	v_exp_f32_e32 v106, v106
	v_exp_f32_e32 v107, v107
	v_add_f32_e32 v104, 1.0, v104
	v_add_f32_e32 v105, 1.0, v105
	v_add_f32_e32 v106, 1.0, v106
	v_add_f32_e32 v107, 1.0, v107
	v_rcp_f32_e32 v104, v104
	v_rcp_f32_e32 v105, v105
	v_rcp_f32_e32 v106, v106
	v_rcp_f32_e32 v107, v107
	v_pk_add_f32 v[102:103], v[102:103], v[250:251]
	v_pk_add_f32 v[100:101], v[100:101], v[248:249]
	v_mul_f32_e32 v102, 0xbfb8aa3b, v102
	v_mul_f32_e32 v100, 0xbfb8aa3b, v100
	v_mul_f32_e32 v101, 0xbfb8aa3b, v101
	v_mul_f32_e32 v103, 0xbfb8aa3b, v103
	v_exp_f32_e32 v100, v100
	v_exp_f32_e32 v101, v101
	v_exp_f32_e32 v102, v102
	v_exp_f32_e32 v103, v103
	v_add_f32_e32 v100, 1.0, v100
	v_add_f32_e32 v101, 1.0, v101
	v_add_f32_e32 v102, 1.0, v102
	v_add_f32_e32 v103, 1.0, v103
	v_rcp_f32_e32 v100, v100
	v_rcp_f32_e32 v101, v101
	v_rcp_f32_e32 v102, v102
	v_rcp_f32_e32 v103, v103
	s_nop 0
	v_mov_b32_dpp v252, v100 row_ror:8 row_mask:0xf bank_mask:0xf
	v_mov_b32_dpp v253, v101 row_ror:8 row_mask:0xf bank_mask:0xf
	v_mov_b32_dpp v254, v102 row_ror:8 row_mask:0xf bank_mask:0xf
	v_mov_b32_dpp v255, v103 row_ror:8 row_mask:0xf bank_mask:0xf
	v_mov_b32_dpp v100, v104 row_ror:8 row_mask:0xf bank_mask:0x3
	v_mov_b32_dpp v101, v105 row_ror:8 row_mask:0xf bank_mask:0x3
	v_mov_b32_dpp v102, v106 row_ror:8 row_mask:0xf bank_mask:0x3
	v_mov_b32_dpp v103, v107 row_ror:8 row_mask:0xf bank_mask:0x3
	v_mov_b32_dpp v104, v252 quad_perm:[0,1,2,3] row_mask:0xf bank_mask:0xc
	v_mov_b32_dpp v105, v253 quad_perm:[0,1,2,3] row_mask:0xf bank_mask:0xc
	v_mov_b32_dpp v106, v254 quad_perm:[0,1,2,3] row_mask:0xf bank_mask:0xc
	v_mov_b32_dpp v107, v255 quad_perm:[0,1,2,3] row_mask:0xf bank_mask:0xc
	global_store_dwordx4 v[144:145], v[104:107], off offset:512
	global_store_dwordx4 v[142:143], v[100:103], off offset:512
	v_lshl_add_u64 v[144:145], s[2:3], 0, v[144:145]
	v_lshl_add_u64 v[142:143], s[2:3], 0, v[142:143]
	v_pk_add_f32 v[98:99], v[98:99], v[238:239]
	v_pk_add_f32 v[96:97], v[96:97], v[236:237]
	v_mul_f32_e32 v98, 0xbfb8aa3b, v98
	v_mul_f32_e32 v96, 0xbfb8aa3b, v96
	v_mul_f32_e32 v97, 0xbfb8aa3b, v97
	v_mul_f32_e32 v99, 0xbfb8aa3b, v99
	v_exp_f32_e32 v96, v96
	v_exp_f32_e32 v97, v97
	v_exp_f32_e32 v98, v98
	v_exp_f32_e32 v99, v99
	v_add_f32_e32 v96, 1.0, v96
	v_add_f32_e32 v97, 1.0, v97
	v_add_f32_e32 v98, 1.0, v98
	v_add_f32_e32 v99, 1.0, v99
	v_rcp_f32_e32 v96, v96
	v_rcp_f32_e32 v97, v97
	v_rcp_f32_e32 v98, v98
	v_rcp_f32_e32 v99, v99
	v_pk_add_f32 v[94:95], v[94:95], v[242:243]
	v_pk_add_f32 v[92:93], v[92:93], v[240:241]
	v_mul_f32_e32 v94, 0xbfb8aa3b, v94
	v_mul_f32_e32 v92, 0xbfb8aa3b, v92
	v_mul_f32_e32 v93, 0xbfb8aa3b, v93
	v_mul_f32_e32 v95, 0xbfb8aa3b, v95
	v_exp_f32_e32 v92, v92
	v_exp_f32_e32 v93, v93
	v_exp_f32_e32 v94, v94
	v_exp_f32_e32 v95, v95
	v_add_f32_e32 v92, 1.0, v92
	v_add_f32_e32 v93, 1.0, v93
	v_add_f32_e32 v94, 1.0, v94
	v_add_f32_e32 v95, 1.0, v95
	v_rcp_f32_e32 v92, v92
	v_rcp_f32_e32 v93, v93
	v_rcp_f32_e32 v94, v94
	v_rcp_f32_e32 v95, v95
	s_nop 0
	v_mov_b32_dpp v252, v92 row_ror:8 row_mask:0xf bank_mask:0xf
	v_mov_b32_dpp v253, v93 row_ror:8 row_mask:0xf bank_mask:0xf
	v_mov_b32_dpp v254, v94 row_ror:8 row_mask:0xf bank_mask:0xf
	v_mov_b32_dpp v255, v95 row_ror:8 row_mask:0xf bank_mask:0xf
	v_mov_b32_dpp v92, v96 row_ror:8 row_mask:0xf bank_mask:0x3
	v_mov_b32_dpp v93, v97 row_ror:8 row_mask:0xf bank_mask:0x3
	v_mov_b32_dpp v94, v98 row_ror:8 row_mask:0xf bank_mask:0x3
	v_mov_b32_dpp v95, v99 row_ror:8 row_mask:0xf bank_mask:0x3
	v_mov_b32_dpp v96, v252 quad_perm:[0,1,2,3] row_mask:0xf bank_mask:0xc
	v_mov_b32_dpp v97, v253 quad_perm:[0,1,2,3] row_mask:0xf bank_mask:0xc
	v_mov_b32_dpp v98, v254 quad_perm:[0,1,2,3] row_mask:0xf bank_mask:0xc
	v_mov_b32_dpp v99, v255 quad_perm:[0,1,2,3] row_mask:0xf bank_mask:0xc
	global_store_dwordx4 v[144:145], v[96:99], off
; __device__ __forceinline__ void epilogue(const f32x4 (&acc)[2][2][4][2], const Unit& u, LAS unsigned char* lds, int wr, int wc, int fr, int fq) {
;     ...
;                     for (int n = 0; n < 2; ++n) { f32x4 v = acc[ai][bj][m][n];
;                         if (mode >= 5) { v += *(const f32x4*)(bias + col0 + bj * HALF + n * 16);
; #pragma unroll
;                             for (int q = 0; q < 4; ++q) { const float sg = __builtin_amdgcn_rcpf(1.f + __expf(-v[q])); v[q] = mode == 5 ? __expf(-0.6065306597126334f * sg) : sg; } }
;                         *(f32x4*)(rowp + bj * HALF + n * 16) = v; }
	global_store_dwordx4 v[142:143], v[92:95], off
	v_pk_add_f32 v[90:91], v[90:91], v[246:247]
	v_pk_add_f32 v[88:89], v[88:89], v[244:245]
	v_mul_f32_e32 v90, 0xbfb8aa3b, v90
	v_mul_f32_e32 v88, 0xbfb8aa3b, v88
	v_mul_f32_e32 v89, 0xbfb8aa3b, v89
	v_mul_f32_e32 v91, 0xbfb8aa3b, v91
	v_exp_f32_e32 v88, v88
	v_exp_f32_e32 v89, v89
	v_exp_f32_e32 v90, v90
	v_exp_f32_e32 v91, v91
	v_add_f32_e32 v88, 1.0, v88
	v_add_f32_e32 v89, 1.0, v89
	v_add_f32_e32 v90, 1.0, v90
	v_add_f32_e32 v91, 1.0, v91
	v_rcp_f32_e32 v88, v88
	v_rcp_f32_e32 v89, v89
	v_rcp_f32_e32 v90, v90
	v_rcp_f32_e32 v91, v91
	v_pk_add_f32 v[86:87], v[86:87], v[250:251]
	v_pk_add_f32 v[84:85], v[84:85], v[248:249]
	v_mul_f32_e32 v86, 0xbfb8aa3b, v86
	v_mul_f32_e32 v84, 0xbfb8aa3b, v84
	v_mul_f32_e32 v85, 0xbfb8aa3b, v85
	v_mul_f32_e32 v87, 0xbfb8aa3b, v87
	v_exp_f32_e32 v84, v84
	v_exp_f32_e32 v85, v85
	v_exp_f32_e32 v86, v86
	v_exp_f32_e32 v87, v87
	v_add_f32_e32 v84, 1.0, v84
	v_add_f32_e32 v85, 1.0, v85
	v_add_f32_e32 v86, 1.0, v86
	v_add_f32_e32 v87, 1.0, v87
	v_rcp_f32_e32 v84, v84
	v_rcp_f32_e32 v85, v85
	v_rcp_f32_e32 v86, v86
	v_rcp_f32_e32 v87, v87
	s_nop 0
	v_mov_b32_dpp v252, v84 row_ror:8 row_mask:0xf bank_mask:0xf
	v_mov_b32_dpp v253, v85 row_ror:8 row_mask:0xf bank_mask:0xf
	v_mov_b32_dpp v254, v86 row_ror:8 row_mask:0xf bank_mask:0xf
	v_mov_b32_dpp v255, v87 row_ror:8 row_mask:0xf bank_mask:0xf
	v_mov_b32_dpp v84, v88 row_ror:8 row_mask:0xf bank_mask:0x3
	v_mov_b32_dpp v85, v89 row_ror:8 row_mask:0xf bank_mask:0x3
	v_mov_b32_dpp v86, v90 row_ror:8 row_mask:0xf bank_mask:0x3
	v_mov_b32_dpp v87, v91 row_ror:8 row_mask:0xf bank_mask:0x3
	v_mov_b32_dpp v88, v252 quad_perm:[0,1,2,3] row_mask:0xf bank_mask:0xc
	v_mov_b32_dpp v89, v253 quad_perm:[0,1,2,3] row_mask:0xf bank_mask:0xc
	v_mov_b32_dpp v90, v254 quad_perm:[0,1,2,3] row_mask:0xf bank_mask:0xc
	v_mov_b32_dpp v91, v255 quad_perm:[0,1,2,3] row_mask:0xf bank_mask:0xc
	global_store_dwordx4 v[144:145], v[88:91], off offset:512
	global_store_dwordx4 v[142:143], v[84:87], off offset:512
	v_lshl_add_u64 v[144:145], s[2:3], 0, v[144:145]
	v_lshl_add_u64 v[142:143], s[2:3], 0, v[142:143]
	v_pk_add_f32 v[82:83], v[82:83], v[238:239]
	v_pk_add_f32 v[80:81], v[80:81], v[236:237]
	v_mul_f32_e32 v82, 0xbfb8aa3b, v82
	v_mul_f32_e32 v80, 0xbfb8aa3b, v80
	v_mul_f32_e32 v81, 0xbfb8aa3b, v81
	v_mul_f32_e32 v83, 0xbfb8aa3b, v83
	v_exp_f32_e32 v80, v80
	v_exp_f32_e32 v81, v81
	v_exp_f32_e32 v82, v82
	v_exp_f32_e32 v83, v83
	v_add_f32_e32 v80, 1.0, v80
	v_add_f32_e32 v81, 1.0, v81
	v_add_f32_e32 v82, 1.0, v82
	v_add_f32_e32 v83, 1.0, v83
	v_rcp_f32_e32 v80, v80
	v_rcp_f32_e32 v81, v81
	v_rcp_f32_e32 v82, v82
	v_rcp_f32_e32 v83, v83
	v_pk_add_f32 v[78:79], v[78:79], v[242:243]
	v_pk_add_f32 v[76:77], v[76:77], v[240:241]
	v_mul_f32_e32 v78, 0xbfb8aa3b, v78
	v_mul_f32_e32 v76, 0xbfb8aa3b, v76
	v_mul_f32_e32 v77, 0xbfb8aa3b, v77
	v_mul_f32_e32 v79, 0xbfb8aa3b, v79
	v_exp_f32_e32 v76, v76
	v_exp_f32_e32 v77, v77
	v_exp_f32_e32 v78, v78
	v_exp_f32_e32 v79, v79
	v_add_f32_e32 v76, 1.0, v76
	v_add_f32_e32 v77, 1.0, v77
	v_add_f32_e32 v78, 1.0, v78
	v_add_f32_e32 v79, 1.0, v79
	v_rcp_f32_e32 v76, v76
	v_rcp_f32_e32 v77, v77
	v_rcp_f32_e32 v78, v78
	v_rcp_f32_e32 v79, v79
	s_nop 0
	v_mov_b32_dpp v252, v76 row_ror:8 row_mask:0xf bank_mask:0xf
	v_mov_b32_dpp v253, v77 row_ror:8 row_mask:0xf bank_mask:0xf
	v_mov_b32_dpp v254, v78 row_ror:8 row_mask:0xf bank_mask:0xf
	v_mov_b32_dpp v255, v79 row_ror:8 row_mask:0xf bank_mask:0xf
	v_mov_b32_dpp v76, v80 row_ror:8 row_mask:0xf bank_mask:0x3
	v_mov_b32_dpp v77, v81 row_ror:8 row_mask:0xf bank_mask:0x3
	v_mov_b32_dpp v78, v82 row_ror:8 row_mask:0xf bank_mask:0x3
	v_mov_b32_dpp v79, v83 row_ror:8 row_mask:0xf bank_mask:0x3
	v_mov_b32_dpp v80, v252 quad_perm:[0,1,2,3] row_mask:0xf bank_mask:0xc
	v_mov_b32_dpp v81, v253 quad_perm:[0,1,2,3] row_mask:0xf bank_mask:0xc
	v_mov_b32_dpp v82, v254 quad_perm:[0,1,2,3] row_mask:0xf bank_mask:0xc
	v_mov_b32_dpp v83, v255 quad_perm:[0,1,2,3] row_mask:0xf bank_mask:0xc
	global_store_dwordx4 v[144:145], v[80:83], off
	global_store_dwordx4 v[142:143], v[76:79], off
	v_pk_add_f32 v[74:75], v[74:75], v[246:247]
	v_pk_add_f32 v[72:73], v[72:73], v[244:245]
	v_mul_f32_e32 v74, 0xbfb8aa3b, v74
	v_mul_f32_e32 v72, 0xbfb8aa3b, v72
	v_mul_f32_e32 v73, 0xbfb8aa3b, v73
	v_mul_f32_e32 v75, 0xbfb8aa3b, v75
	v_exp_f32_e32 v72, v72
	v_exp_f32_e32 v73, v73
	v_exp_f32_e32 v74, v74
	v_exp_f32_e32 v75, v75
	v_add_f32_e32 v72, 1.0, v72
	v_add_f32_e32 v73, 1.0, v73
	v_add_f32_e32 v74, 1.0, v74
	v_add_f32_e32 v75, 1.0, v75
	v_rcp_f32_e32 v72, v72
	v_rcp_f32_e32 v73, v73
	v_rcp_f32_e32 v74, v74
	v_rcp_f32_e32 v75, v75
	v_pk_add_f32 v[70:71], v[70:71], v[250:251]
	v_pk_add_f32 v[68:69], v[68:69], v[248:249]
	v_mul_f32_e32 v70, 0xbfb8aa3b, v70
	v_mul_f32_e32 v68, 0xbfb8aa3b, v68
	v_mul_f32_e32 v69, 0xbfb8aa3b, v69
	v_mul_f32_e32 v71, 0xbfb8aa3b, v71
	v_exp_f32_e32 v68, v68
	v_exp_f32_e32 v69, v69
	v_exp_f32_e32 v70, v70
	v_exp_f32_e32 v71, v71
	v_add_f32_e32 v68, 1.0, v68
	v_add_f32_e32 v69, 1.0, v69
	v_add_f32_e32 v70, 1.0, v70
	v_add_f32_e32 v71, 1.0, v71
	v_rcp_f32_e32 v68, v68
	v_rcp_f32_e32 v69, v69
	v_rcp_f32_e32 v70, v70
	v_rcp_f32_e32 v71, v71
	s_nop 0
	v_mov_b32_dpp v252, v68 row_ror:8 row_mask:0xf bank_mask:0xf
	v_mov_b32_dpp v253, v69 row_ror:8 row_mask:0xf bank_mask:0xf
	v_mov_b32_dpp v254, v70 row_ror:8 row_mask:0xf bank_mask:0xf
	v_mov_b32_dpp v255, v71 row_ror:8 row_mask:0xf bank_mask:0xf
	v_mov_b32_dpp v68, v72 row_ror:8 row_mask:0xf bank_mask:0x3
	v_mov_b32_dpp v69, v73 row_ror:8 row_mask:0xf bank_mask:0x3
	v_mov_b32_dpp v70, v74 row_ror:8 row_mask:0xf bank_mask:0x3
; __device__ __forceinline__ void epilogue(const f32x4 (&acc)[2][2][4][2], const Unit& u, LAS unsigned char* lds, int wr, int wc, int fr, int fq) {
;     ...
;                     for (int n = 0; n < 2; ++n) { f32x4 v = acc[ai][bj][m][n];
;                         if (mode >= 5) { v += *(const f32x4*)(bias + col0 + bj * HALF + n * 16);
; #pragma unroll
;                             for (int q = 0; q < 4; ++q) { const float sg = __builtin_amdgcn_rcpf(1.f + __expf(-v[q])); v[q] = mode == 5 ? __expf(-0.6065306597126334f * sg) : sg; } }
;                         *(f32x4*)(rowp + bj * HALF + n * 16) = v; }
	v_mov_b32_dpp v71, v75 row_ror:8 row_mask:0xf bank_mask:0x3
	v_mov_b32_dpp v72, v252 quad_perm:[0,1,2,3] row_mask:0xf bank_mask:0xc
	v_mov_b32_dpp v73, v253 quad_perm:[0,1,2,3] row_mask:0xf bank_mask:0xc
	v_mov_b32_dpp v74, v254 quad_perm:[0,1,2,3] row_mask:0xf bank_mask:0xc
	v_mov_b32_dpp v75, v255 quad_perm:[0,1,2,3] row_mask:0xf bank_mask:0xc
	global_store_dwordx4 v[144:145], v[72:75], off offset:512
	global_store_dwordx4 v[142:143], v[68:71], off offset:512
	v_lshl_add_u64 v[144:145], s[2:3], 2, v[144:145]
	v_lshl_add_u64 v[142:143], s[2:3], 2, v[142:143]
	v_lshl_add_u64 v[144:145], s[2:3], 0, v[144:145]
	v_lshl_add_u64 v[142:143], s[2:3], 0, v[142:143]
	v_pk_add_f32 v[66:67], v[66:67], v[238:239]
	v_pk_add_f32 v[64:65], v[64:65], v[236:237]
	v_mul_f32_e32 v66, 0xbfb8aa3b, v66
	v_mul_f32_e32 v64, 0xbfb8aa3b, v64
	v_mul_f32_e32 v65, 0xbfb8aa3b, v65
	v_mul_f32_e32 v67, 0xbfb8aa3b, v67
	v_exp_f32_e32 v64, v64
	v_exp_f32_e32 v65, v65
	v_exp_f32_e32 v66, v66
	v_exp_f32_e32 v67, v67
	v_add_f32_e32 v64, 1.0, v64
	v_add_f32_e32 v65, 1.0, v65
	v_add_f32_e32 v66, 1.0, v66
	v_add_f32_e32 v67, 1.0, v67
	v_rcp_f32_e32 v64, v64
	v_rcp_f32_e32 v65, v65
	v_rcp_f32_e32 v66, v66
	v_rcp_f32_e32 v67, v67
	v_pk_add_f32 v[62:63], v[62:63], v[242:243]
	v_pk_add_f32 v[60:61], v[60:61], v[240:241]
	v_mul_f32_e32 v62, 0xbfb8aa3b, v62
	v_mul_f32_e32 v60, 0xbfb8aa3b, v60
	v_mul_f32_e32 v61, 0xbfb8aa3b, v61
	v_mul_f32_e32 v63, 0xbfb8aa3b, v63
	v_exp_f32_e32 v60, v60
	v_exp_f32_e32 v61, v61
	v_exp_f32_e32 v62, v62
	v_exp_f32_e32 v63, v63
	v_add_f32_e32 v60, 1.0, v60
	v_add_f32_e32 v61, 1.0, v61
	v_add_f32_e32 v62, 1.0, v62
	v_add_f32_e32 v63, 1.0, v63
	v_rcp_f32_e32 v60, v60
	v_rcp_f32_e32 v61, v61
	v_rcp_f32_e32 v62, v62
	v_rcp_f32_e32 v63, v63
	s_nop 0
	v_mov_b32_dpp v252, v60 row_ror:8 row_mask:0xf bank_mask:0xf
	v_mov_b32_dpp v253, v61 row_ror:8 row_mask:0xf bank_mask:0xf
	v_mov_b32_dpp v254, v62 row_ror:8 row_mask:0xf bank_mask:0xf
	v_mov_b32_dpp v255, v63 row_ror:8 row_mask:0xf bank_mask:0xf
	v_mov_b32_dpp v60, v64 row_ror:8 row_mask:0xf bank_mask:0x3
	v_mov_b32_dpp v61, v65 row_ror:8 row_mask:0xf bank_mask:0x3
	v_mov_b32_dpp v62, v66 row_ror:8 row_mask:0xf bank_mask:0x3
	v_mov_b32_dpp v63, v67 row_ror:8 row_mask:0xf bank_mask:0x3
	v_mov_b32_dpp v64, v252 quad_perm:[0,1,2,3] row_mask:0xf bank_mask:0xc
	v_mov_b32_dpp v65, v253 quad_perm:[0,1,2,3] row_mask:0xf bank_mask:0xc
	v_mov_b32_dpp v66, v254 quad_perm:[0,1,2,3] row_mask:0xf bank_mask:0xc
	v_mov_b32_dpp v67, v255 quad_perm:[0,1,2,3] row_mask:0xf bank_mask:0xc
	global_store_dwordx4 v[144:145], v[64:67], off
	global_store_dwordx4 v[142:143], v[60:63], off
	v_pk_add_f32 v[58:59], v[58:59], v[246:247]
	v_pk_add_f32 v[56:57], v[56:57], v[244:245]
	v_mul_f32_e32 v58, 0xbfb8aa3b, v58
	v_mul_f32_e32 v56, 0xbfb8aa3b, v56
	v_mul_f32_e32 v57, 0xbfb8aa3b, v57
	v_mul_f32_e32 v59, 0xbfb8aa3b, v59
	v_exp_f32_e32 v56, v56
	v_exp_f32_e32 v57, v57
	v_exp_f32_e32 v58, v58
	v_exp_f32_e32 v59, v59
	v_add_f32_e32 v56, 1.0, v56
	v_add_f32_e32 v57, 1.0, v57
	v_add_f32_e32 v58, 1.0, v58
	v_add_f32_e32 v59, 1.0, v59
	v_rcp_f32_e32 v56, v56
	v_rcp_f32_e32 v57, v57
	v_rcp_f32_e32 v58, v58
	v_rcp_f32_e32 v59, v59
	v_pk_add_f32 v[54:55], v[54:55], v[250:251]
	v_pk_add_f32 v[52:53], v[52:53], v[248:249]
	v_mul_f32_e32 v54, 0xbfb8aa3b, v54
	v_mul_f32_e32 v52, 0xbfb8aa3b, v52
	v_mul_f32_e32 v53, 0xbfb8aa3b, v53
	v_mul_f32_e32 v55, 0xbfb8aa3b, v55
	v_exp_f32_e32 v52, v52
	v_exp_f32_e32 v53, v53
	v_exp_f32_e32 v54, v54
	v_exp_f32_e32 v55, v55
	v_add_f32_e32 v52, 1.0, v52
	v_add_f32_e32 v53, 1.0, v53
	v_add_f32_e32 v54, 1.0, v54
	v_add_f32_e32 v55, 1.0, v55
	v_rcp_f32_e32 v52, v52
	v_rcp_f32_e32 v53, v53
	v_rcp_f32_e32 v54, v54
	v_rcp_f32_e32 v55, v55
	s_nop 0
	v_mov_b32_dpp v252, v52 row_ror:8 row_mask:0xf bank_mask:0xf
	v_mov_b32_dpp v253, v53 row_ror:8 row_mask:0xf bank_mask:0xf
	v_mov_b32_dpp v254, v54 row_ror:8 row_mask:0xf bank_mask:0xf
	v_mov_b32_dpp v255, v55 row_ror:8 row_mask:0xf bank_mask:0xf
	v_mov_b32_dpp v52, v56 row_ror:8 row_mask:0xf bank_mask:0x3
	v_mov_b32_dpp v53, v57 row_ror:8 row_mask:0xf bank_mask:0x3
	v_mov_b32_dpp v54, v58 row_ror:8 row_mask:0xf bank_mask:0x3
	v_mov_b32_dpp v55, v59 row_ror:8 row_mask:0xf bank_mask:0x3
	v_mov_b32_dpp v56, v252 quad_perm:[0,1,2,3] row_mask:0xf bank_mask:0xc
	v_mov_b32_dpp v57, v253 quad_perm:[0,1,2,3] row_mask:0xf bank_mask:0xc
	v_mov_b32_dpp v58, v254 quad_perm:[0,1,2,3] row_mask:0xf bank_mask:0xc
	v_mov_b32_dpp v59, v255 quad_perm:[0,1,2,3] row_mask:0xf bank_mask:0xc
	global_store_dwordx4 v[144:145], v[56:59], off offset:512
	global_store_dwordx4 v[142:143], v[52:55], off offset:512
	v_lshl_add_u64 v[144:145], s[2:3], 0, v[144:145]
	v_lshl_add_u64 v[142:143], s[2:3], 0, v[142:143]
	v_pk_add_f32 v[50:51], v[50:51], v[238:239]
	v_pk_add_f32 v[48:49], v[48:49], v[236:237]
	v_mul_f32_e32 v50, 0xbfb8aa3b, v50
	v_mul_f32_e32 v48, 0xbfb8aa3b, v48
	v_mul_f32_e32 v49, 0xbfb8aa3b, v49
	v_mul_f32_e32 v51, 0xbfb8aa3b, v51
	v_exp_f32_e32 v48, v48
	v_exp_f32_e32 v49, v49
	v_exp_f32_e32 v50, v50
	v_exp_f32_e32 v51, v51
	v_add_f32_e32 v48, 1.0, v48
	v_add_f32_e32 v49, 1.0, v49
	v_add_f32_e32 v50, 1.0, v50
	v_add_f32_e32 v51, 1.0, v51
	v_rcp_f32_e32 v48, v48
	v_rcp_f32_e32 v49, v49
	v_rcp_f32_e32 v50, v50
	v_rcp_f32_e32 v51, v51
	v_pk_add_f32 v[46:47], v[46:47], v[242:243]
	v_pk_add_f32 v[44:45], v[44:45], v[240:241]
	v_mul_f32_e32 v46, 0xbfb8aa3b, v46
	v_mul_f32_e32 v44, 0xbfb8aa3b, v44
	v_mul_f32_e32 v45, 0xbfb8aa3b, v45
	v_mul_f32_e32 v47, 0xbfb8aa3b, v47
	v_exp_f32_e32 v44, v44
	v_exp_f32_e32 v45, v45
	v_exp_f32_e32 v46, v46
	v_exp_f32_e32 v47, v47
	v_add_f32_e32 v44, 1.0, v44
; __device__ __forceinline__ void epilogue(const f32x4 (&acc)[2][2][4][2], const Unit& u, LAS unsigned char* lds, int wr, int wc, int fr, int fq) {
;     ...
;                     for (int n = 0; n < 2; ++n) { f32x4 v = acc[ai][bj][m][n];
;                         if (mode >= 5) { v += *(const f32x4*)(bias + col0 + bj * HALF + n * 16);
; #pragma unroll
;                             for (int q = 0; q < 4; ++q) { const float sg = __builtin_amdgcn_rcpf(1.f + __expf(-v[q])); v[q] = mode == 5 ? __expf(-0.6065306597126334f * sg) : sg; } }
;                         *(f32x4*)(rowp + bj * HALF + n * 16) = v; }
	v_add_f32_e32 v45, 1.0, v45
	v_add_f32_e32 v46, 1.0, v46
	v_add_f32_e32 v47, 1.0, v47
	v_rcp_f32_e32 v44, v44
	v_rcp_f32_e32 v45, v45
	v_rcp_f32_e32 v46, v46
	v_rcp_f32_e32 v47, v47
	s_nop 0
	v_mov_b32_dpp v252, v44 row_ror:8 row_mask:0xf bank_mask:0xf
	v_mov_b32_dpp v253, v45 row_ror:8 row_mask:0xf bank_mask:0xf
	v_mov_b32_dpp v254, v46 row_ror:8 row_mask:0xf bank_mask:0xf
	v_mov_b32_dpp v255, v47 row_ror:8 row_mask:0xf bank_mask:0xf
	v_mov_b32_dpp v44, v48 row_ror:8 row_mask:0xf bank_mask:0x3
	v_mov_b32_dpp v45, v49 row_ror:8 row_mask:0xf bank_mask:0x3
	v_mov_b32_dpp v46, v50 row_ror:8 row_mask:0xf bank_mask:0x3
	v_mov_b32_dpp v47, v51 row_ror:8 row_mask:0xf bank_mask:0x3
	v_mov_b32_dpp v48, v252 quad_perm:[0,1,2,3] row_mask:0xf bank_mask:0xc
	v_mov_b32_dpp v49, v253 quad_perm:[0,1,2,3] row_mask:0xf bank_mask:0xc
	v_mov_b32_dpp v50, v254 quad_perm:[0,1,2,3] row_mask:0xf bank_mask:0xc
	v_mov_b32_dpp v51, v255 quad_perm:[0,1,2,3] row_mask:0xf bank_mask:0xc
	global_store_dwordx4 v[144:145], v[48:51], off
	global_store_dwordx4 v[142:143], v[44:47], off
	v_pk_add_f32 v[42:43], v[42:43], v[246:247]
	v_pk_add_f32 v[40:41], v[40:41], v[244:245]
	v_mul_f32_e32 v42, 0xbfb8aa3b, v42
	v_mul_f32_e32 v40, 0xbfb8aa3b, v40
	v_mul_f32_e32 v41, 0xbfb8aa3b, v41
	v_mul_f32_e32 v43, 0xbfb8aa3b, v43
	v_exp_f32_e32 v40, v40
	v_exp_f32_e32 v41, v41
	v_exp_f32_e32 v42, v42
	v_exp_f32_e32 v43, v43
	v_add_f32_e32 v40, 1.0, v40
	v_add_f32_e32 v41, 1.0, v41
	v_add_f32_e32 v42, 1.0, v42
	v_add_f32_e32 v43, 1.0, v43
	v_rcp_f32_e32 v40, v40
	v_rcp_f32_e32 v41, v41
	v_rcp_f32_e32 v42, v42
	v_rcp_f32_e32 v43, v43
	v_pk_add_f32 v[38:39], v[38:39], v[250:251]
	v_pk_add_f32 v[36:37], v[36:37], v[248:249]
	v_mul_f32_e32 v38, 0xbfb8aa3b, v38
	v_mul_f32_e32 v36, 0xbfb8aa3b, v36
	v_mul_f32_e32 v37, 0xbfb8aa3b, v37
	v_mul_f32_e32 v39, 0xbfb8aa3b, v39
	v_exp_f32_e32 v36, v36
	v_exp_f32_e32 v37, v37
	v_exp_f32_e32 v38, v38
	v_exp_f32_e32 v39, v39
	v_add_f32_e32 v36, 1.0, v36
	v_add_f32_e32 v37, 1.0, v37
	v_add_f32_e32 v38, 1.0, v38
	v_add_f32_e32 v39, 1.0, v39
	v_rcp_f32_e32 v36, v36
	v_rcp_f32_e32 v37, v37
	v_rcp_f32_e32 v38, v38
	v_rcp_f32_e32 v39, v39
	s_nop 0
	v_mov_b32_dpp v252, v36 row_ror:8 row_mask:0xf bank_mask:0xf
	v_mov_b32_dpp v253, v37 row_ror:8 row_mask:0xf bank_mask:0xf
	v_mov_b32_dpp v254, v38 row_ror:8 row_mask:0xf bank_mask:0xf
	v_mov_b32_dpp v255, v39 row_ror:8 row_mask:0xf bank_mask:0xf
	v_mov_b32_dpp v36, v40 row_ror:8 row_mask:0xf bank_mask:0x3
	v_mov_b32_dpp v37, v41 row_ror:8 row_mask:0xf bank_mask:0x3
	v_mov_b32_dpp v38, v42 row_ror:8 row_mask:0xf bank_mask:0x3
	v_mov_b32_dpp v39, v43 row_ror:8 row_mask:0xf bank_mask:0x3
	v_mov_b32_dpp v40, v252 quad_perm:[0,1,2,3] row_mask:0xf bank_mask:0xc
	v_mov_b32_dpp v41, v253 quad_perm:[0,1,2,3] row_mask:0xf bank_mask:0xc
	v_mov_b32_dpp v42, v254 quad_perm:[0,1,2,3] row_mask:0xf bank_mask:0xc
	v_mov_b32_dpp v43, v255 quad_perm:[0,1,2,3] row_mask:0xf bank_mask:0xc
	global_store_dwordx4 v[144:145], v[40:43], off offset:512
	global_store_dwordx4 v[142:143], v[36:39], off offset:512
	v_lshl_add_u64 v[144:145], s[2:3], 0, v[144:145]
	v_lshl_add_u64 v[142:143], s[2:3], 0, v[142:143]
	v_pk_add_f32 v[34:35], v[34:35], v[238:239]
	v_pk_add_f32 v[32:33], v[32:33], v[236:237]
	v_mul_f32_e32 v34, 0xbfb8aa3b, v34
	v_mul_f32_e32 v32, 0xbfb8aa3b, v32
	v_mul_f32_e32 v33, 0xbfb8aa3b, v33
	v_mul_f32_e32 v35, 0xbfb8aa3b, v35
	v_exp_f32_e32 v32, v32
	v_exp_f32_e32 v33, v33
	v_exp_f32_e32 v34, v34
	v_exp_f32_e32 v35, v35
	v_add_f32_e32 v32, 1.0, v32
	v_add_f32_e32 v33, 1.0, v33
	v_add_f32_e32 v34, 1.0, v34
	v_add_f32_e32 v35, 1.0, v35
	v_rcp_f32_e32 v32, v32
	v_rcp_f32_e32 v33, v33
	v_rcp_f32_e32 v34, v34
	v_rcp_f32_e32 v35, v35
	v_pk_add_f32 v[30:31], v[30:31], v[242:243]
	v_pk_add_f32 v[28:29], v[28:29], v[240:241]
	v_mul_f32_e32 v30, 0xbfb8aa3b, v30
	v_mul_f32_e32 v28, 0xbfb8aa3b, v28
	v_mul_f32_e32 v29, 0xbfb8aa3b, v29
	v_mul_f32_e32 v31, 0xbfb8aa3b, v31
	v_exp_f32_e32 v28, v28
	v_exp_f32_e32 v29, v29
	v_exp_f32_e32 v30, v30
	v_exp_f32_e32 v31, v31
	v_add_f32_e32 v28, 1.0, v28
	v_add_f32_e32 v29, 1.0, v29
	v_add_f32_e32 v30, 1.0, v30
	v_add_f32_e32 v31, 1.0, v31
	v_rcp_f32_e32 v28, v28
	v_rcp_f32_e32 v29, v29
	v_rcp_f32_e32 v30, v30
	v_rcp_f32_e32 v31, v31
	s_nop 0
	v_mov_b32_dpp v252, v28 row_ror:8 row_mask:0xf bank_mask:0xf
	v_mov_b32_dpp v253, v29 row_ror:8 row_mask:0xf bank_mask:0xf
	v_mov_b32_dpp v254, v30 row_ror:8 row_mask:0xf bank_mask:0xf
	v_mov_b32_dpp v255, v31 row_ror:8 row_mask:0xf bank_mask:0xf
	v_mov_b32_dpp v28, v32 row_ror:8 row_mask:0xf bank_mask:0x3
	v_mov_b32_dpp v29, v33 row_ror:8 row_mask:0xf bank_mask:0x3
	v_mov_b32_dpp v30, v34 row_ror:8 row_mask:0xf bank_mask:0x3
	v_mov_b32_dpp v31, v35 row_ror:8 row_mask:0xf bank_mask:0x3
	v_mov_b32_dpp v32, v252 quad_perm:[0,1,2,3] row_mask:0xf bank_mask:0xc
	v_mov_b32_dpp v33, v253 quad_perm:[0,1,2,3] row_mask:0xf bank_mask:0xc
	v_mov_b32_dpp v34, v254 quad_perm:[0,1,2,3] row_mask:0xf bank_mask:0xc
	v_mov_b32_dpp v35, v255 quad_perm:[0,1,2,3] row_mask:0xf bank_mask:0xc
	global_store_dwordx4 v[144:145], v[32:35], off
	global_store_dwordx4 v[142:143], v[28:31], off
	v_pk_add_f32 v[26:27], v[26:27], v[246:247]
	v_pk_add_f32 v[24:25], v[24:25], v[244:245]
	v_mul_f32_e32 v26, 0xbfb8aa3b, v26
	v_mul_f32_e32 v24, 0xbfb8aa3b, v24
	v_mul_f32_e32 v25, 0xbfb8aa3b, v25
	v_mul_f32_e32 v27, 0xbfb8aa3b, v27
	v_exp_f32_e32 v24, v24
	v_exp_f32_e32 v25, v25
	v_exp_f32_e32 v26, v26
	v_exp_f32_e32 v27, v27
	v_add_f32_e32 v24, 1.0, v24
	v_add_f32_e32 v25, 1.0, v25
	v_add_f32_e32 v26, 1.0, v26
	v_add_f32_e32 v27, 1.0, v27
	v_rcp_f32_e32 v24, v24
	v_rcp_f32_e32 v25, v25
	v_rcp_f32_e32 v26, v26
; __device__ __forceinline__ void epilogue(const f32x4 (&acc)[2][2][4][2], const Unit& u, LAS unsigned char* lds, int wr, int wc, int fr, int fq) {
;     ...
;                     for (int n = 0; n < 2; ++n) { f32x4 v = acc[ai][bj][m][n];
;                         if (mode >= 5) { v += *(const f32x4*)(bias + col0 + bj * HALF + n * 16);
; #pragma unroll
;                             for (int q = 0; q < 4; ++q) { const float sg = __builtin_amdgcn_rcpf(1.f + __expf(-v[q])); v[q] = mode == 5 ? __expf(-0.6065306597126334f * sg) : sg; } }
;                         *(f32x4*)(rowp + bj * HALF + n * 16) = v; }
	v_rcp_f32_e32 v27, v27
	v_pk_add_f32 v[22:23], v[22:23], v[250:251]
	v_pk_add_f32 v[20:21], v[20:21], v[248:249]
	v_mul_f32_e32 v22, 0xbfb8aa3b, v22
	v_mul_f32_e32 v20, 0xbfb8aa3b, v20
	v_mul_f32_e32 v21, 0xbfb8aa3b, v21
	v_mul_f32_e32 v23, 0xbfb8aa3b, v23
	v_exp_f32_e32 v20, v20
	v_exp_f32_e32 v21, v21
	v_exp_f32_e32 v22, v22
	v_exp_f32_e32 v23, v23
	v_add_f32_e32 v20, 1.0, v20
	v_add_f32_e32 v21, 1.0, v21
	v_add_f32_e32 v22, 1.0, v22
	v_add_f32_e32 v23, 1.0, v23
	v_rcp_f32_e32 v20, v20
	v_rcp_f32_e32 v21, v21
	v_rcp_f32_e32 v22, v22
	v_rcp_f32_e32 v23, v23
	s_nop 0
	v_mov_b32_dpp v252, v20 row_ror:8 row_mask:0xf bank_mask:0xf
	v_mov_b32_dpp v253, v21 row_ror:8 row_mask:0xf bank_mask:0xf
	v_mov_b32_dpp v254, v22 row_ror:8 row_mask:0xf bank_mask:0xf
	v_mov_b32_dpp v255, v23 row_ror:8 row_mask:0xf bank_mask:0xf
	v_mov_b32_dpp v20, v24 row_ror:8 row_mask:0xf bank_mask:0x3
	v_mov_b32_dpp v21, v25 row_ror:8 row_mask:0xf bank_mask:0x3
	v_mov_b32_dpp v22, v26 row_ror:8 row_mask:0xf bank_mask:0x3
	v_mov_b32_dpp v23, v27 row_ror:8 row_mask:0xf bank_mask:0x3
	v_mov_b32_dpp v24, v252 quad_perm:[0,1,2,3] row_mask:0xf bank_mask:0xc
	v_mov_b32_dpp v25, v253 quad_perm:[0,1,2,3] row_mask:0xf bank_mask:0xc
	v_mov_b32_dpp v26, v254 quad_perm:[0,1,2,3] row_mask:0xf bank_mask:0xc
	v_mov_b32_dpp v27, v255 quad_perm:[0,1,2,3] row_mask:0xf bank_mask:0xc
	global_store_dwordx4 v[144:145], v[24:27], off offset:512
	global_store_dwordx4 v[142:143], v[20:23], off offset:512
	v_lshl_add_u64 v[144:145], s[2:3], 0, v[144:145]
	v_lshl_add_u64 v[142:143], s[2:3], 0, v[142:143]
	v_pk_add_f32 v[18:19], v[18:19], v[238:239]
	v_pk_add_f32 v[16:17], v[16:17], v[236:237]
	v_mul_f32_e32 v18, 0xbfb8aa3b, v18
	v_mul_f32_e32 v16, 0xbfb8aa3b, v16
	v_mul_f32_e32 v17, 0xbfb8aa3b, v17
	v_mul_f32_e32 v19, 0xbfb8aa3b, v19
	v_exp_f32_e32 v16, v16
	v_exp_f32_e32 v17, v17
	v_exp_f32_e32 v18, v18
	v_exp_f32_e32 v19, v19
	v_add_f32_e32 v16, 1.0, v16
	v_add_f32_e32 v17, 1.0, v17
	v_add_f32_e32 v18, 1.0, v18
	v_add_f32_e32 v19, 1.0, v19
	v_rcp_f32_e32 v16, v16
	v_rcp_f32_e32 v17, v17
	v_rcp_f32_e32 v18, v18
	v_rcp_f32_e32 v19, v19
	v_pk_add_f32 v[14:15], v[14:15], v[242:243]
	v_pk_add_f32 v[12:13], v[12:13], v[240:241]
	v_mul_f32_e32 v14, 0xbfb8aa3b, v14
	v_mul_f32_e32 v12, 0xbfb8aa3b, v12
	v_mul_f32_e32 v13, 0xbfb8aa3b, v13
	v_mul_f32_e32 v15, 0xbfb8aa3b, v15
	v_exp_f32_e32 v12, v12
	v_exp_f32_e32 v13, v13
	v_exp_f32_e32 v14, v14
	v_exp_f32_e32 v15, v15
	v_add_f32_e32 v12, 1.0, v12
	v_add_f32_e32 v13, 1.0, v13
	v_add_f32_e32 v14, 1.0, v14
	v_add_f32_e32 v15, 1.0, v15
	v_rcp_f32_e32 v12, v12
	v_rcp_f32_e32 v13, v13
	v_rcp_f32_e32 v14, v14
	v_rcp_f32_e32 v15, v15
	s_nop 0
	v_mov_b32_dpp v252, v12 row_ror:8 row_mask:0xf bank_mask:0xf
	v_mov_b32_dpp v253, v13 row_ror:8 row_mask:0xf bank_mask:0xf
	v_mov_b32_dpp v254, v14 row_ror:8 row_mask:0xf bank_mask:0xf
	v_mov_b32_dpp v255, v15 row_ror:8 row_mask:0xf bank_mask:0xf
	v_mov_b32_dpp v12, v16 row_ror:8 row_mask:0xf bank_mask:0x3
	v_mov_b32_dpp v13, v17 row_ror:8 row_mask:0xf bank_mask:0x3
	v_mov_b32_dpp v14, v18 row_ror:8 row_mask:0xf bank_mask:0x3
	v_mov_b32_dpp v15, v19 row_ror:8 row_mask:0xf bank_mask:0x3
	v_mov_b32_dpp v16, v252 quad_perm:[0,1,2,3] row_mask:0xf bank_mask:0xc
	v_mov_b32_dpp v17, v253 quad_perm:[0,1,2,3] row_mask:0xf bank_mask:0xc
	v_mov_b32_dpp v18, v254 quad_perm:[0,1,2,3] row_mask:0xf bank_mask:0xc
	v_mov_b32_dpp v19, v255 quad_perm:[0,1,2,3] row_mask:0xf bank_mask:0xc
	global_store_dwordx4 v[144:145], v[16:19], off
	global_store_dwordx4 v[142:143], v[12:15], off
	v_pk_add_f32 v[10:11], v[10:11], v[246:247]
	v_pk_add_f32 v[8:9], v[8:9], v[244:245]
	v_mul_f32_e32 v10, 0xbfb8aa3b, v10
	v_mul_f32_e32 v8, 0xbfb8aa3b, v8
	v_mul_f32_e32 v9, 0xbfb8aa3b, v9
	v_mul_f32_e32 v11, 0xbfb8aa3b, v11
	v_exp_f32_e32 v8, v8
	v_exp_f32_e32 v9, v9
	v_exp_f32_e32 v10, v10
	v_exp_f32_e32 v11, v11
	v_add_f32_e32 v8, 1.0, v8
	v_add_f32_e32 v9, 1.0, v9
	v_add_f32_e32 v10, 1.0, v10
	v_add_f32_e32 v11, 1.0, v11
	v_rcp_f32_e32 v8, v8
	v_rcp_f32_e32 v9, v9
	v_rcp_f32_e32 v10, v10
	v_rcp_f32_e32 v11, v11
	v_pk_add_f32 v[6:7], v[6:7], v[250:251]
	v_pk_add_f32 v[4:5], v[4:5], v[248:249]
	v_mul_f32_e32 v6, 0xbfb8aa3b, v6
	v_mul_f32_e32 v4, 0xbfb8aa3b, v4
	v_mul_f32_e32 v5, 0xbfb8aa3b, v5
	v_mul_f32_e32 v7, 0xbfb8aa3b, v7
	v_exp_f32_e32 v4, v4
	v_exp_f32_e32 v5, v5
	v_exp_f32_e32 v6, v6
	v_exp_f32_e32 v7, v7
	v_add_f32_e32 v4, 1.0, v4
	v_add_f32_e32 v5, 1.0, v5
	v_add_f32_e32 v6, 1.0, v6
	v_add_f32_e32 v7, 1.0, v7
	v_rcp_f32_e32 v4, v4
	v_rcp_f32_e32 v5, v5
	v_rcp_f32_e32 v6, v6
	v_rcp_f32_e32 v7, v7
	s_nop 0
	v_mov_b32_dpp v252, v4 row_ror:8 row_mask:0xf bank_mask:0xf
	v_mov_b32_dpp v253, v5 row_ror:8 row_mask:0xf bank_mask:0xf
	v_mov_b32_dpp v254, v6 row_ror:8 row_mask:0xf bank_mask:0xf
	v_mov_b32_dpp v255, v7 row_ror:8 row_mask:0xf bank_mask:0xf
	v_mov_b32_dpp v4, v8 row_ror:8 row_mask:0xf bank_mask:0x3
	v_mov_b32_dpp v5, v9 row_ror:8 row_mask:0xf bank_mask:0x3
	v_mov_b32_dpp v6, v10 row_ror:8 row_mask:0xf bank_mask:0x3
	v_mov_b32_dpp v7, v11 row_ror:8 row_mask:0xf bank_mask:0x3
	v_mov_b32_dpp v8, v252 quad_perm:[0,1,2,3] row_mask:0xf bank_mask:0xc
	v_mov_b32_dpp v9, v253 quad_perm:[0,1,2,3] row_mask:0xf bank_mask:0xc
	v_mov_b32_dpp v10, v254 quad_perm:[0,1,2,3] row_mask:0xf bank_mask:0xc
	v_mov_b32_dpp v11, v255 quad_perm:[0,1,2,3] row_mask:0xf bank_mask:0xc
	global_store_dwordx4 v[144:145], v[8:11], off offset:512
	global_store_dwordx4 v[142:143], v[4:7], off offset:512
	s_branch .LBB0_1310
; __device__ __forceinline__ void epilogue(const f32x4 (&acc)[2][2][4][2], const Unit& u, LAS unsigned char* lds, int wr, int wc, int fr, int fq) {
;     ...
;                     for (int n = 0; n < 2; ++n) { f32x4 v = acc[ai][bj][m][n];
;                         if (mode >= 5) { v += *(const f32x4*)(bias + col0 + bj * HALF + n * 16);
; #pragma unroll
;                             for (int q = 0; q < 4; ++q) { const float sg = __builtin_amdgcn_rcpf(1.f + __expf(-v[q])); v[q] = mode == 5 ? __expf(-0.6065306597126334f * sg) : sg; } }
;                         *(f32x4*)(rowp + bj * HALF + n * 16) = v; }
.Lepi_f5:
	v_pk_add_f32 v[130:131], v[130:131], v[238:239]
	v_pk_add_f32 v[128:129], v[128:129], v[236:237]
	v_mul_f32_e32 v130, 0xbfb8aa3b, v130
	v_mul_f32_e32 v128, 0xbfb8aa3b, v128
	v_mul_f32_e32 v129, 0xbfb8aa3b, v129
	v_mul_f32_e32 v131, 0xbfb8aa3b, v131
	v_exp_f32_e32 v128, v128
	v_exp_f32_e32 v129, v129
	v_exp_f32_e32 v130, v130
	v_exp_f32_e32 v131, v131
	v_add_f32_e32 v128, 1.0, v128
	v_add_f32_e32 v129, 1.0, v129
	v_add_f32_e32 v130, 1.0, v130
	v_add_f32_e32 v131, 1.0, v131
	v_rcp_f32_e32 v128, v128
	v_rcp_f32_e32 v129, v129
	v_rcp_f32_e32 v130, v130
	v_rcp_f32_e32 v131, v131
	v_mul_f32_e32 v128, 0xbf1b4598, v128
	v_mul_f32_e32 v129, 0xbf1b4598, v129
	v_mul_f32_e32 v130, 0xbf1b4598, v130
	v_mul_f32_e32 v131, 0xbf1b4598, v131
	v_mul_f32_e32 v128, 0x3fb8aa3b, v128
	v_mul_f32_e32 v129, 0x3fb8aa3b, v129
	v_mul_f32_e32 v130, 0x3fb8aa3b, v130
	v_mul_f32_e32 v131, 0x3fb8aa3b, v131
	v_exp_f32_e32 v128, v128
	v_exp_f32_e32 v129, v129
	v_exp_f32_e32 v130, v130
	v_exp_f32_e32 v131, v131
	v_pk_add_f32 v[126:127], v[126:127], v[242:243]
	v_pk_add_f32 v[124:125], v[124:125], v[240:241]
	v_mul_f32_e32 v126, 0xbfb8aa3b, v126
	v_mul_f32_e32 v124, 0xbfb8aa3b, v124
	v_mul_f32_e32 v125, 0xbfb8aa3b, v125
	v_mul_f32_e32 v127, 0xbfb8aa3b, v127
	v_exp_f32_e32 v124, v124
	v_exp_f32_e32 v125, v125
	v_exp_f32_e32 v126, v126
	v_exp_f32_e32 v127, v127
	v_add_f32_e32 v124, 1.0, v124
	v_add_f32_e32 v125, 1.0, v125
	v_add_f32_e32 v126, 1.0, v126
	v_add_f32_e32 v127, 1.0, v127
	v_rcp_f32_e32 v124, v124
	v_rcp_f32_e32 v125, v125
	v_rcp_f32_e32 v126, v126
	v_rcp_f32_e32 v127, v127
	v_mul_f32_e32 v124, 0xbf1b4598, v124
	v_mul_f32_e32 v125, 0xbf1b4598, v125
	v_mul_f32_e32 v126, 0xbf1b4598, v126
	v_mul_f32_e32 v127, 0xbf1b4598, v127
	v_mul_f32_e32 v124, 0x3fb8aa3b, v124
	v_mul_f32_e32 v125, 0x3fb8aa3b, v125
	v_mul_f32_e32 v126, 0x3fb8aa3b, v126
	v_mul_f32_e32 v127, 0x3fb8aa3b, v127
	v_exp_f32_e32 v124, v124
	v_exp_f32_e32 v125, v125
	v_exp_f32_e32 v126, v126
	v_exp_f32_e32 v127, v127
	s_nop 0
	v_mov_b32_dpp v252, v124 row_ror:8 row_mask:0xf bank_mask:0xf
	v_mov_b32_dpp v253, v125 row_ror:8 row_mask:0xf bank_mask:0xf
	v_mov_b32_dpp v254, v126 row_ror:8 row_mask:0xf bank_mask:0xf
	v_mov_b32_dpp v255, v127 row_ror:8 row_mask:0xf bank_mask:0xf
	v_mov_b32_dpp v124, v128 row_ror:8 row_mask:0xf bank_mask:0x3
	v_mov_b32_dpp v125, v129 row_ror:8 row_mask:0xf bank_mask:0x3
	v_mov_b32_dpp v126, v130 row_ror:8 row_mask:0xf bank_mask:0x3
	v_mov_b32_dpp v127, v131 row_ror:8 row_mask:0xf bank_mask:0x3
	v_mov_b32_dpp v128, v252 quad_perm:[0,1,2,3] row_mask:0xf bank_mask:0xc
	v_mov_b32_dpp v129, v253 quad_perm:[0,1,2,3] row_mask:0xf bank_mask:0xc
	v_mov_b32_dpp v130, v254 quad_perm:[0,1,2,3] row_mask:0xf bank_mask:0xc
	v_mov_b32_dpp v131, v255 quad_perm:[0,1,2,3] row_mask:0xf bank_mask:0xc
	global_store_dwordx4 v[144:145], v[128:131], off
	global_store_dwordx4 v[142:143], v[124:127], off
	v_pk_add_f32 v[122:123], v[122:123], v[246:247]
	v_pk_add_f32 v[120:121], v[120:121], v[244:245]
	v_mul_f32_e32 v122, 0xbfb8aa3b, v122
	v_mul_f32_e32 v120, 0xbfb8aa3b, v120
	v_mul_f32_e32 v121, 0xbfb8aa3b, v121
	v_mul_f32_e32 v123, 0xbfb8aa3b, v123
	v_exp_f32_e32 v120, v120
	v_exp_f32_e32 v121, v121
	v_exp_f32_e32 v122, v122
	v_exp_f32_e32 v123, v123
	v_add_f32_e32 v120, 1.0, v120
	v_add_f32_e32 v121, 1.0, v121
	v_add_f32_e32 v122, 1.0, v122
	v_add_f32_e32 v123, 1.0, v123
	v_rcp_f32_e32 v120, v120
	v_rcp_f32_e32 v121, v121
	v_rcp_f32_e32 v122, v122
	v_rcp_f32_e32 v123, v123
	v_mul_f32_e32 v120, 0xbf1b4598, v120
	v_mul_f32_e32 v121, 0xbf1b4598, v121
	v_mul_f32_e32 v122, 0xbf1b4598, v122
	v_mul_f32_e32 v123, 0xbf1b4598, v123
	v_mul_f32_e32 v120, 0x3fb8aa3b, v120
	v_mul_f32_e32 v121, 0x3fb8aa3b, v121
	v_mul_f32_e32 v122, 0x3fb8aa3b, v122
	v_mul_f32_e32 v123, 0x3fb8aa3b, v123
	v_exp_f32_e32 v120, v120
	v_exp_f32_e32 v121, v121
	v_exp_f32_e32 v122, v122
	v_exp_f32_e32 v123, v123
	v_pk_add_f32 v[118:119], v[118:119], v[250:251]
	v_pk_add_f32 v[116:117], v[116:117], v[248:249]
	v_mul_f32_e32 v118, 0xbfb8aa3b, v118
	v_mul_f32_e32 v116, 0xbfb8aa3b, v116
	v_mul_f32_e32 v117, 0xbfb8aa3b, v117
	v_mul_f32_e32 v119, 0xbfb8aa3b, v119
	v_exp_f32_e32 v116, v116
	v_exp_f32_e32 v117, v117
	v_exp_f32_e32 v118, v118
	v_exp_f32_e32 v119, v119
	v_add_f32_e32 v116, 1.0, v116
	v_add_f32_e32 v117, 1.0, v117
	v_add_f32_e32 v118, 1.0, v118
	v_add_f32_e32 v119, 1.0, v119
	v_rcp_f32_e32 v116, v116
	v_rcp_f32_e32 v117, v117
	v_rcp_f32_e32 v118, v118
	v_rcp_f32_e32 v119, v119
	v_mul_f32_e32 v116, 0xbf1b4598, v116
	v_mul_f32_e32 v117, 0xbf1b4598, v117
	v_mul_f32_e32 v118, 0xbf1b4598, v118
	v_mul_f32_e32 v119, 0xbf1b4598, v119
	v_mul_f32_e32 v116, 0x3fb8aa3b, v116
	v_mul_f32_e32 v117, 0x3fb8aa3b, v117
	v_mul_f32_e32 v118, 0x3fb8aa3b, v118
	v_mul_f32_e32 v119, 0x3fb8aa3b, v119
	v_exp_f32_e32 v116, v116
	v_exp_f32_e32 v117, v117
	v_exp_f32_e32 v118, v118
	v_exp_f32_e32 v119, v119
	s_nop 0
	v_mov_b32_dpp v252, v116 row_ror:8 row_mask:0xf bank_mask:0xf
	v_mov_b32_dpp v253, v117 row_ror:8 row_mask:0xf bank_mask:0xf
	v_mov_b32_dpp v254, v118 row_ror:8 row_mask:0xf bank_mask:0xf
	v_mov_b32_dpp v255, v119 row_ror:8 row_mask:0xf bank_mask:0xf
	v_mov_b32_dpp v116, v120 row_ror:8 row_mask:0xf bank_mask:0x3
	v_mov_b32_dpp v117, v121 row_ror:8 row_mask:0xf bank_mask:0x3
	v_mov_b32_dpp v118, v122 row_ror:8 row_mask:0xf bank_mask:0x3
	v_mov_b32_dpp v119, v123 row_ror:8 row_mask:0xf bank_mask:0x3
	v_mov_b32_dpp v120, v252 quad_perm:[0,1,2,3] row_mask:0xf bank_mask:0xc
	v_mov_b32_dpp v121, v253 quad_perm:[0,1,2,3] row_mask:0xf bank_mask:0xc
	v_mov_b32_dpp v122, v254 quad_perm:[0,1,2,3] row_mask:0xf bank_mask:0xc
; __device__ __forceinline__ void epilogue(const f32x4 (&acc)[2][2][4][2], const Unit& u, LAS unsigned char* lds, int wr, int wc, int fr, int fq) {
;     ...
;                     for (int n = 0; n < 2; ++n) { f32x4 v = acc[ai][bj][m][n];
;                         if (mode >= 5) { v += *(const f32x4*)(bias + col0 + bj * HALF + n * 16);
; #pragma unroll
;                             for (int q = 0; q < 4; ++q) { const float sg = __builtin_amdgcn_rcpf(1.f + __expf(-v[q])); v[q] = mode == 5 ? __expf(-0.6065306597126334f * sg) : sg; } }
;                         *(f32x4*)(rowp + bj * HALF + n * 16) = v; }
	v_mov_b32_dpp v123, v255 quad_perm:[0,1,2,3] row_mask:0xf bank_mask:0xc
	global_store_dwordx4 v[144:145], v[120:123], off offset:512
	global_store_dwordx4 v[142:143], v[116:119], off offset:512
	v_lshl_add_u64 v[144:145], s[2:3], 0, v[144:145]
	v_lshl_add_u64 v[142:143], s[2:3], 0, v[142:143]
	v_pk_add_f32 v[114:115], v[114:115], v[238:239]
	v_pk_add_f32 v[112:113], v[112:113], v[236:237]
	v_mul_f32_e32 v114, 0xbfb8aa3b, v114
	v_mul_f32_e32 v112, 0xbfb8aa3b, v112
	v_mul_f32_e32 v113, 0xbfb8aa3b, v113
	v_mul_f32_e32 v115, 0xbfb8aa3b, v115
	v_exp_f32_e32 v112, v112
	v_exp_f32_e32 v113, v113
	v_exp_f32_e32 v114, v114
	v_exp_f32_e32 v115, v115
	v_add_f32_e32 v112, 1.0, v112
	v_add_f32_e32 v113, 1.0, v113
	v_add_f32_e32 v114, 1.0, v114
	v_add_f32_e32 v115, 1.0, v115
	v_rcp_f32_e32 v112, v112
	v_rcp_f32_e32 v113, v113
	v_rcp_f32_e32 v114, v114
	v_rcp_f32_e32 v115, v115
	v_mul_f32_e32 v112, 0xbf1b4598, v112
	v_mul_f32_e32 v113, 0xbf1b4598, v113
	v_mul_f32_e32 v114, 0xbf1b4598, v114
	v_mul_f32_e32 v115, 0xbf1b4598, v115
	v_mul_f32_e32 v112, 0x3fb8aa3b, v112
	v_mul_f32_e32 v113, 0x3fb8aa3b, v113
	v_mul_f32_e32 v114, 0x3fb8aa3b, v114
	v_mul_f32_e32 v115, 0x3fb8aa3b, v115
	v_exp_f32_e32 v112, v112
	v_exp_f32_e32 v113, v113
	v_exp_f32_e32 v114, v114
	v_exp_f32_e32 v115, v115
	v_pk_add_f32 v[110:111], v[110:111], v[242:243]
	v_pk_add_f32 v[108:109], v[108:109], v[240:241]
	v_mul_f32_e32 v110, 0xbfb8aa3b, v110
	v_mul_f32_e32 v108, 0xbfb8aa3b, v108
	v_mul_f32_e32 v109, 0xbfb8aa3b, v109
	v_mul_f32_e32 v111, 0xbfb8aa3b, v111
	v_exp_f32_e32 v108, v108
	v_exp_f32_e32 v109, v109
	v_exp_f32_e32 v110, v110
	v_exp_f32_e32 v111, v111
	v_add_f32_e32 v108, 1.0, v108
	v_add_f32_e32 v109, 1.0, v109
	v_add_f32_e32 v110, 1.0, v110
	v_add_f32_e32 v111, 1.0, v111
	v_rcp_f32_e32 v108, v108
	v_rcp_f32_e32 v109, v109
	v_rcp_f32_e32 v110, v110
	v_rcp_f32_e32 v111, v111
	v_mul_f32_e32 v108, 0xbf1b4598, v108
	v_mul_f32_e32 v109, 0xbf1b4598, v109
	v_mul_f32_e32 v110, 0xbf1b4598, v110
	v_mul_f32_e32 v111, 0xbf1b4598, v111
	v_mul_f32_e32 v108, 0x3fb8aa3b, v108
	v_mul_f32_e32 v109, 0x3fb8aa3b, v109
	v_mul_f32_e32 v110, 0x3fb8aa3b, v110
	v_mul_f32_e32 v111, 0x3fb8aa3b, v111
	v_exp_f32_e32 v108, v108
	v_exp_f32_e32 v109, v109
	v_exp_f32_e32 v110, v110
	v_exp_f32_e32 v111, v111
	s_nop 0
	v_mov_b32_dpp v252, v108 row_ror:8 row_mask:0xf bank_mask:0xf
	v_mov_b32_dpp v253, v109 row_ror:8 row_mask:0xf bank_mask:0xf
	v_mov_b32_dpp v254, v110 row_ror:8 row_mask:0xf bank_mask:0xf
	v_mov_b32_dpp v255, v111 row_ror:8 row_mask:0xf bank_mask:0xf
	v_mov_b32_dpp v108, v112 row_ror:8 row_mask:0xf bank_mask:0x3
	v_mov_b32_dpp v109, v113 row_ror:8 row_mask:0xf bank_mask:0x3
	v_mov_b32_dpp v110, v114 row_ror:8 row_mask:0xf bank_mask:0x3
	v_mov_b32_dpp v111, v115 row_ror:8 row_mask:0xf bank_mask:0x3
	v_mov_b32_dpp v112, v252 quad_perm:[0,1,2,3] row_mask:0xf bank_mask:0xc
	v_mov_b32_dpp v113, v253 quad_perm:[0,1,2,3] row_mask:0xf bank_mask:0xc
	v_mov_b32_dpp v114, v254 quad_perm:[0,1,2,3] row_mask:0xf bank_mask:0xc
	v_mov_b32_dpp v115, v255 quad_perm:[0,1,2,3] row_mask:0xf bank_mask:0xc
	global_store_dwordx4 v[144:145], v[112:115], off
	global_store_dwordx4 v[142:143], v[108:111], off
	v_pk_add_f32 v[106:107], v[106:107], v[246:247]
	v_pk_add_f32 v[104:105], v[104:105], v[244:245]
	v_mul_f32_e32 v106, 0xbfb8aa3b, v106
	v_mul_f32_e32 v104, 0xbfb8aa3b, v104
	v_mul_f32_e32 v105, 0xbfb8aa3b, v105
	v_mul_f32_e32 v107, 0xbfb8aa3b, v107
	v_exp_f32_e32 v104, v104
	v_exp_f32_e32 v105, v105
	v_exp_f32_e32 v106, v106
	v_exp_f32_e32 v107, v107
	v_add_f32_e32 v104, 1.0, v104
	v_add_f32_e32 v105, 1.0, v105
	v_add_f32_e32 v106, 1.0, v106
	v_add_f32_e32 v107, 1.0, v107
	v_rcp_f32_e32 v104, v104
	v_rcp_f32_e32 v105, v105
	v_rcp_f32_e32 v106, v106
	v_rcp_f32_e32 v107, v107
	v_mul_f32_e32 v104, 0xbf1b4598, v104
	v_mul_f32_e32 v105, 0xbf1b4598, v105
	v_mul_f32_e32 v106, 0xbf1b4598, v106
	v_mul_f32_e32 v107, 0xbf1b4598, v107
	v_mul_f32_e32 v104, 0x3fb8aa3b, v104
	v_mul_f32_e32 v105, 0x3fb8aa3b, v105
	v_mul_f32_e32 v106, 0x3fb8aa3b, v106
	v_mul_f32_e32 v107, 0x3fb8aa3b, v107
	v_exp_f32_e32 v104, v104
	v_exp_f32_e32 v105, v105
	v_exp_f32_e32 v106, v106
	v_exp_f32_e32 v107, v107
	v_pk_add_f32 v[102:103], v[102:103], v[250:251]
	v_pk_add_f32 v[100:101], v[100:101], v[248:249]
	v_mul_f32_e32 v102, 0xbfb8aa3b, v102
	v_mul_f32_e32 v100, 0xbfb8aa3b, v100
	v_mul_f32_e32 v101, 0xbfb8aa3b, v101
	v_mul_f32_e32 v103, 0xbfb8aa3b, v103
	v_exp_f32_e32 v100, v100
	v_exp_f32_e32 v101, v101
	v_exp_f32_e32 v102, v102
	v_exp_f32_e32 v103, v103
	v_add_f32_e32 v100, 1.0, v100
	v_add_f32_e32 v101, 1.0, v101
	v_add_f32_e32 v102, 1.0, v102
	v_add_f32_e32 v103, 1.0, v103
	v_rcp_f32_e32 v100, v100
	v_rcp_f32_e32 v101, v101
	v_rcp_f32_e32 v102, v102
	v_rcp_f32_e32 v103, v103
	v_mul_f32_e32 v100, 0xbf1b4598, v100
	v_mul_f32_e32 v101, 0xbf1b4598, v101
	v_mul_f32_e32 v102, 0xbf1b4598, v102
	v_mul_f32_e32 v103, 0xbf1b4598, v103
	v_mul_f32_e32 v100, 0x3fb8aa3b, v100
	v_mul_f32_e32 v101, 0x3fb8aa3b, v101
	v_mul_f32_e32 v102, 0x3fb8aa3b, v102
	v_mul_f32_e32 v103, 0x3fb8aa3b, v103
	v_exp_f32_e32 v100, v100
	v_exp_f32_e32 v101, v101
	v_exp_f32_e32 v102, v102
	v_exp_f32_e32 v103, v103
	s_nop 0
	v_mov_b32_dpp v252, v100 row_ror:8 row_mask:0xf bank_mask:0xf
	v_mov_b32_dpp v253, v101 row_ror:8 row_mask:0xf bank_mask:0xf
	v_mov_b32_dpp v254, v102 row_ror:8 row_mask:0xf bank_mask:0xf
	v_mov_b32_dpp v255, v103 row_ror:8 row_mask:0xf bank_mask:0xf
	v_mov_b32_dpp v100, v104 row_ror:8 row_mask:0xf bank_mask:0x3
	v_mov_b32_dpp v101, v105 row_ror:8 row_mask:0xf bank_mask:0x3
	v_mov_b32_dpp v102, v106 row_ror:8 row_mask:0xf bank_mask:0x3
; __device__ __forceinline__ void epilogue(const f32x4 (&acc)[2][2][4][2], const Unit& u, LAS unsigned char* lds, int wr, int wc, int fr, int fq) {
;     ...
;                     for (int n = 0; n < 2; ++n) { f32x4 v = acc[ai][bj][m][n];
;                         if (mode >= 5) { v += *(const f32x4*)(bias + col0 + bj * HALF + n * 16);
; #pragma unroll
;                             for (int q = 0; q < 4; ++q) { const float sg = __builtin_amdgcn_rcpf(1.f + __expf(-v[q])); v[q] = mode == 5 ? __expf(-0.6065306597126334f * sg) : sg; } }
;                         *(f32x4*)(rowp + bj * HALF + n * 16) = v; }
	v_mov_b32_dpp v103, v107 row_ror:8 row_mask:0xf bank_mask:0x3
	v_mov_b32_dpp v104, v252 quad_perm:[0,1,2,3] row_mask:0xf bank_mask:0xc
	v_mov_b32_dpp v105, v253 quad_perm:[0,1,2,3] row_mask:0xf bank_mask:0xc
	v_mov_b32_dpp v106, v254 quad_perm:[0,1,2,3] row_mask:0xf bank_mask:0xc
	v_mov_b32_dpp v107, v255 quad_perm:[0,1,2,3] row_mask:0xf bank_mask:0xc
	global_store_dwordx4 v[144:145], v[104:107], off offset:512
	global_store_dwordx4 v[142:143], v[100:103], off offset:512
	v_lshl_add_u64 v[144:145], s[2:3], 0, v[144:145]
	v_lshl_add_u64 v[142:143], s[2:3], 0, v[142:143]
	v_pk_add_f32 v[98:99], v[98:99], v[238:239]
	v_pk_add_f32 v[96:97], v[96:97], v[236:237]
	v_mul_f32_e32 v98, 0xbfb8aa3b, v98
	v_mul_f32_e32 v96, 0xbfb8aa3b, v96
	v_mul_f32_e32 v97, 0xbfb8aa3b, v97
	v_mul_f32_e32 v99, 0xbfb8aa3b, v99
	v_exp_f32_e32 v96, v96
	v_exp_f32_e32 v97, v97
	v_exp_f32_e32 v98, v98
	v_exp_f32_e32 v99, v99
	v_add_f32_e32 v96, 1.0, v96
	v_add_f32_e32 v97, 1.0, v97
	v_add_f32_e32 v98, 1.0, v98
	v_add_f32_e32 v99, 1.0, v99
	v_rcp_f32_e32 v96, v96
	v_rcp_f32_e32 v97, v97
	v_rcp_f32_e32 v98, v98
	v_rcp_f32_e32 v99, v99
	v_mul_f32_e32 v96, 0xbf1b4598, v96
	v_mul_f32_e32 v97, 0xbf1b4598, v97
	v_mul_f32_e32 v98, 0xbf1b4598, v98
	v_mul_f32_e32 v99, 0xbf1b4598, v99
	v_mul_f32_e32 v96, 0x3fb8aa3b, v96
	v_mul_f32_e32 v97, 0x3fb8aa3b, v97
	v_mul_f32_e32 v98, 0x3fb8aa3b, v98
	v_mul_f32_e32 v99, 0x3fb8aa3b, v99
	v_exp_f32_e32 v96, v96
	v_exp_f32_e32 v97, v97
	v_exp_f32_e32 v98, v98
	v_exp_f32_e32 v99, v99
	v_pk_add_f32 v[94:95], v[94:95], v[242:243]
	v_pk_add_f32 v[92:93], v[92:93], v[240:241]
	v_mul_f32_e32 v94, 0xbfb8aa3b, v94
	v_mul_f32_e32 v92, 0xbfb8aa3b, v92
	v_mul_f32_e32 v93, 0xbfb8aa3b, v93
	v_mul_f32_e32 v95, 0xbfb8aa3b, v95
	v_exp_f32_e32 v92, v92
	v_exp_f32_e32 v93, v93
	v_exp_f32_e32 v94, v94
	v_exp_f32_e32 v95, v95
	v_add_f32_e32 v92, 1.0, v92
	v_add_f32_e32 v93, 1.0, v93
	v_add_f32_e32 v94, 1.0, v94
	v_add_f32_e32 v95, 1.0, v95
	v_rcp_f32_e32 v92, v92
	v_rcp_f32_e32 v93, v93
	v_rcp_f32_e32 v94, v94
	v_rcp_f32_e32 v95, v95
	v_mul_f32_e32 v92, 0xbf1b4598, v92
	v_mul_f32_e32 v93, 0xbf1b4598, v93
	v_mul_f32_e32 v94, 0xbf1b4598, v94
	v_mul_f32_e32 v95, 0xbf1b4598, v95
	v_mul_f32_e32 v92, 0x3fb8aa3b, v92
	v_mul_f32_e32 v93, 0x3fb8aa3b, v93
	v_mul_f32_e32 v94, 0x3fb8aa3b, v94
	v_mul_f32_e32 v95, 0x3fb8aa3b, v95
	v_exp_f32_e32 v92, v92
	v_exp_f32_e32 v93, v93
	v_exp_f32_e32 v94, v94
	v_exp_f32_e32 v95, v95
	s_nop 0
	v_mov_b32_dpp v252, v92 row_ror:8 row_mask:0xf bank_mask:0xf
	v_mov_b32_dpp v253, v93 row_ror:8 row_mask:0xf bank_mask:0xf
	v_mov_b32_dpp v254, v94 row_ror:8 row_mask:0xf bank_mask:0xf
	v_mov_b32_dpp v255, v95 row_ror:8 row_mask:0xf bank_mask:0xf
	v_mov_b32_dpp v92, v96 row_ror:8 row_mask:0xf bank_mask:0x3
	v_mov_b32_dpp v93, v97 row_ror:8 row_mask:0xf bank_mask:0x3
	v_mov_b32_dpp v94, v98 row_ror:8 row_mask:0xf bank_mask:0x3
	v_mov_b32_dpp v95, v99 row_ror:8 row_mask:0xf bank_mask:0x3
	v_mov_b32_dpp v96, v252 quad_perm:[0,1,2,3] row_mask:0xf bank_mask:0xc
	v_mov_b32_dpp v97, v253 quad_perm:[0,1,2,3] row_mask:0xf bank_mask:0xc
	v_mov_b32_dpp v98, v254 quad_perm:[0,1,2,3] row_mask:0xf bank_mask:0xc
	v_mov_b32_dpp v99, v255 quad_perm:[0,1,2,3] row_mask:0xf bank_mask:0xc
	global_store_dwordx4 v[144:145], v[96:99], off
	global_store_dwordx4 v[142:143], v[92:95], off
	v_pk_add_f32 v[90:91], v[90:91], v[246:247]
	v_pk_add_f32 v[88:89], v[88:89], v[244:245]
	v_mul_f32_e32 v90, 0xbfb8aa3b, v90
	v_mul_f32_e32 v88, 0xbfb8aa3b, v88
	v_mul_f32_e32 v89, 0xbfb8aa3b, v89
	v_mul_f32_e32 v91, 0xbfb8aa3b, v91
	v_exp_f32_e32 v88, v88
	v_exp_f32_e32 v89, v89
	v_exp_f32_e32 v90, v90
	v_exp_f32_e32 v91, v91
	v_add_f32_e32 v88, 1.0, v88
	v_add_f32_e32 v89, 1.0, v89
	v_add_f32_e32 v90, 1.0, v90
	v_add_f32_e32 v91, 1.0, v91
	v_rcp_f32_e32 v88, v88
	v_rcp_f32_e32 v89, v89
	v_rcp_f32_e32 v90, v90
	v_rcp_f32_e32 v91, v91
	v_mul_f32_e32 v88, 0xbf1b4598, v88
	v_mul_f32_e32 v89, 0xbf1b4598, v89
	v_mul_f32_e32 v90, 0xbf1b4598, v90
	v_mul_f32_e32 v91, 0xbf1b4598, v91
	v_mul_f32_e32 v88, 0x3fb8aa3b, v88
	v_mul_f32_e32 v89, 0x3fb8aa3b, v89
	v_mul_f32_e32 v90, 0x3fb8aa3b, v90
	v_mul_f32_e32 v91, 0x3fb8aa3b, v91
	v_exp_f32_e32 v88, v88
	v_exp_f32_e32 v89, v89
	v_exp_f32_e32 v90, v90
	v_exp_f32_e32 v91, v91
	v_pk_add_f32 v[86:87], v[86:87], v[250:251]
	v_pk_add_f32 v[84:85], v[84:85], v[248:249]
	v_mul_f32_e32 v86, 0xbfb8aa3b, v86
	v_mul_f32_e32 v84, 0xbfb8aa3b, v84
	v_mul_f32_e32 v85, 0xbfb8aa3b, v85
	v_mul_f32_e32 v87, 0xbfb8aa3b, v87
	v_exp_f32_e32 v84, v84
	v_exp_f32_e32 v85, v85
	v_exp_f32_e32 v86, v86
	v_exp_f32_e32 v87, v87
	v_add_f32_e32 v84, 1.0, v84
	v_add_f32_e32 v85, 1.0, v85
	v_add_f32_e32 v86, 1.0, v86
	v_add_f32_e32 v87, 1.0, v87
	v_rcp_f32_e32 v84, v84
	v_rcp_f32_e32 v85, v85
	v_rcp_f32_e32 v86, v86
	v_rcp_f32_e32 v87, v87
	v_mul_f32_e32 v84, 0xbf1b4598, v84
	v_mul_f32_e32 v85, 0xbf1b4598, v85
	v_mul_f32_e32 v86, 0xbf1b4598, v86
	v_mul_f32_e32 v87, 0xbf1b4598, v87
	v_mul_f32_e32 v84, 0x3fb8aa3b, v84
	v_mul_f32_e32 v85, 0x3fb8aa3b, v85
	v_mul_f32_e32 v86, 0x3fb8aa3b, v86
	v_mul_f32_e32 v87, 0x3fb8aa3b, v87
	v_exp_f32_e32 v84, v84
	v_exp_f32_e32 v85, v85
	v_exp_f32_e32 v86, v86
	v_exp_f32_e32 v87, v87
	s_nop 0
	v_mov_b32_dpp v252, v84 row_ror:8 row_mask:0xf bank_mask:0xf
	v_mov_b32_dpp v253, v85 row_ror:8 row_mask:0xf bank_mask:0xf
	v_mov_b32_dpp v254, v86 row_ror:8 row_mask:0xf bank_mask:0xf
	v_mov_b32_dpp v255, v87 row_ror:8 row_mask:0xf bank_mask:0xf
	v_mov_b32_dpp v84, v88 row_ror:8 row_mask:0xf bank_mask:0x3
	v_mov_b32_dpp v85, v89 row_ror:8 row_mask:0xf bank_mask:0x3
	v_mov_b32_dpp v86, v90 row_ror:8 row_mask:0xf bank_mask:0x3
	v_mov_b32_dpp v87, v91 row_ror:8 row_mask:0xf bank_mask:0x3
; __device__ __forceinline__ void epilogue(const f32x4 (&acc)[2][2][4][2], const Unit& u, LAS unsigned char* lds, int wr, int wc, int fr, int fq) {
;     ...
;                     for (int n = 0; n < 2; ++n) { f32x4 v = acc[ai][bj][m][n];
;                         if (mode >= 5) { v += *(const f32x4*)(bias + col0 + bj * HALF + n * 16);
; #pragma unroll
;                             for (int q = 0; q < 4; ++q) { const float sg = __builtin_amdgcn_rcpf(1.f + __expf(-v[q])); v[q] = mode == 5 ? __expf(-0.6065306597126334f * sg) : sg; } }
;                         *(f32x4*)(rowp + bj * HALF + n * 16) = v; }
	v_mov_b32_dpp v88, v252 quad_perm:[0,1,2,3] row_mask:0xf bank_mask:0xc
	v_mov_b32_dpp v89, v253 quad_perm:[0,1,2,3] row_mask:0xf bank_mask:0xc
	v_mov_b32_dpp v90, v254 quad_perm:[0,1,2,3] row_mask:0xf bank_mask:0xc
	v_mov_b32_dpp v91, v255 quad_perm:[0,1,2,3] row_mask:0xf bank_mask:0xc
	global_store_dwordx4 v[144:145], v[88:91], off offset:512
	global_store_dwordx4 v[142:143], v[84:87], off offset:512
	v_lshl_add_u64 v[144:145], s[2:3], 0, v[144:145]
	v_lshl_add_u64 v[142:143], s[2:3], 0, v[142:143]
	v_pk_add_f32 v[82:83], v[82:83], v[238:239]
	v_pk_add_f32 v[80:81], v[80:81], v[236:237]
	v_mul_f32_e32 v82, 0xbfb8aa3b, v82
	v_mul_f32_e32 v80, 0xbfb8aa3b, v80
	v_mul_f32_e32 v81, 0xbfb8aa3b, v81
	v_mul_f32_e32 v83, 0xbfb8aa3b, v83
	v_exp_f32_e32 v80, v80
	v_exp_f32_e32 v81, v81
	v_exp_f32_e32 v82, v82
	v_exp_f32_e32 v83, v83
	v_add_f32_e32 v80, 1.0, v80
	v_add_f32_e32 v81, 1.0, v81
	v_add_f32_e32 v82, 1.0, v82
	v_add_f32_e32 v83, 1.0, v83
	v_rcp_f32_e32 v80, v80
	v_rcp_f32_e32 v81, v81
	v_rcp_f32_e32 v82, v82
	v_rcp_f32_e32 v83, v83
	v_mul_f32_e32 v80, 0xbf1b4598, v80
	v_mul_f32_e32 v81, 0xbf1b4598, v81
	v_mul_f32_e32 v82, 0xbf1b4598, v82
	v_mul_f32_e32 v83, 0xbf1b4598, v83
	v_mul_f32_e32 v80, 0x3fb8aa3b, v80
	v_mul_f32_e32 v81, 0x3fb8aa3b, v81
	v_mul_f32_e32 v82, 0x3fb8aa3b, v82
	v_mul_f32_e32 v83, 0x3fb8aa3b, v83
	v_exp_f32_e32 v80, v80
	v_exp_f32_e32 v81, v81
	v_exp_f32_e32 v82, v82
	v_exp_f32_e32 v83, v83
	v_pk_add_f32 v[78:79], v[78:79], v[242:243]
	v_pk_add_f32 v[76:77], v[76:77], v[240:241]
	v_mul_f32_e32 v78, 0xbfb8aa3b, v78
	v_mul_f32_e32 v76, 0xbfb8aa3b, v76
	v_mul_f32_e32 v77, 0xbfb8aa3b, v77
	v_mul_f32_e32 v79, 0xbfb8aa3b, v79
	v_exp_f32_e32 v76, v76
	v_exp_f32_e32 v77, v77
	v_exp_f32_e32 v78, v78
	v_exp_f32_e32 v79, v79
	v_add_f32_e32 v76, 1.0, v76
	v_add_f32_e32 v77, 1.0, v77
	v_add_f32_e32 v78, 1.0, v78
	v_add_f32_e32 v79, 1.0, v79
	v_rcp_f32_e32 v76, v76
	v_rcp_f32_e32 v77, v77
	v_rcp_f32_e32 v78, v78
	v_rcp_f32_e32 v79, v79
	v_mul_f32_e32 v76, 0xbf1b4598, v76
	v_mul_f32_e32 v77, 0xbf1b4598, v77
	v_mul_f32_e32 v78, 0xbf1b4598, v78
	v_mul_f32_e32 v79, 0xbf1b4598, v79
	v_mul_f32_e32 v76, 0x3fb8aa3b, v76
	v_mul_f32_e32 v77, 0x3fb8aa3b, v77
	v_mul_f32_e32 v78, 0x3fb8aa3b, v78
	v_mul_f32_e32 v79, 0x3fb8aa3b, v79
	v_exp_f32_e32 v76, v76
	v_exp_f32_e32 v77, v77
	v_exp_f32_e32 v78, v78
	v_exp_f32_e32 v79, v79
	s_nop 0
	v_mov_b32_dpp v252, v76 row_ror:8 row_mask:0xf bank_mask:0xf
	v_mov_b32_dpp v253, v77 row_ror:8 row_mask:0xf bank_mask:0xf
	v_mov_b32_dpp v254, v78 row_ror:8 row_mask:0xf bank_mask:0xf
	v_mov_b32_dpp v255, v79 row_ror:8 row_mask:0xf bank_mask:0xf
	v_mov_b32_dpp v76, v80 row_ror:8 row_mask:0xf bank_mask:0x3
	v_mov_b32_dpp v77, v81 row_ror:8 row_mask:0xf bank_mask:0x3
	v_mov_b32_dpp v78, v82 row_ror:8 row_mask:0xf bank_mask:0x3
	v_mov_b32_dpp v79, v83 row_ror:8 row_mask:0xf bank_mask:0x3
	v_mov_b32_dpp v80, v252 quad_perm:[0,1,2,3] row_mask:0xf bank_mask:0xc
	v_mov_b32_dpp v81, v253 quad_perm:[0,1,2,3] row_mask:0xf bank_mask:0xc
	v_mov_b32_dpp v82, v254 quad_perm:[0,1,2,3] row_mask:0xf bank_mask:0xc
	v_mov_b32_dpp v83, v255 quad_perm:[0,1,2,3] row_mask:0xf bank_mask:0xc
	global_store_dwordx4 v[144:145], v[80:83], off
	global_store_dwordx4 v[142:143], v[76:79], off
	v_pk_add_f32 v[74:75], v[74:75], v[246:247]
	v_pk_add_f32 v[72:73], v[72:73], v[244:245]
	v_mul_f32_e32 v74, 0xbfb8aa3b, v74
	v_mul_f32_e32 v72, 0xbfb8aa3b, v72
	v_mul_f32_e32 v73, 0xbfb8aa3b, v73
	v_mul_f32_e32 v75, 0xbfb8aa3b, v75
	v_exp_f32_e32 v72, v72
	v_exp_f32_e32 v73, v73
	v_exp_f32_e32 v74, v74
	v_exp_f32_e32 v75, v75
	v_add_f32_e32 v72, 1.0, v72
	v_add_f32_e32 v73, 1.0, v73
	v_add_f32_e32 v74, 1.0, v74
	v_add_f32_e32 v75, 1.0, v75
	v_rcp_f32_e32 v72, v72
	v_rcp_f32_e32 v73, v73
	v_rcp_f32_e32 v74, v74
	v_rcp_f32_e32 v75, v75
	v_mul_f32_e32 v72, 0xbf1b4598, v72
	v_mul_f32_e32 v73, 0xbf1b4598, v73
	v_mul_f32_e32 v74, 0xbf1b4598, v74
	v_mul_f32_e32 v75, 0xbf1b4598, v75
	v_mul_f32_e32 v72, 0x3fb8aa3b, v72
	v_mul_f32_e32 v73, 0x3fb8aa3b, v73
	v_mul_f32_e32 v74, 0x3fb8aa3b, v74
	v_mul_f32_e32 v75, 0x3fb8aa3b, v75
	v_exp_f32_e32 v72, v72
	v_exp_f32_e32 v73, v73
	v_exp_f32_e32 v74, v74
	v_exp_f32_e32 v75, v75
	v_pk_add_f32 v[70:71], v[70:71], v[250:251]
	v_pk_add_f32 v[68:69], v[68:69], v[248:249]
	v_mul_f32_e32 v70, 0xbfb8aa3b, v70
	v_mul_f32_e32 v68, 0xbfb8aa3b, v68
	v_mul_f32_e32 v69, 0xbfb8aa3b, v69
	v_mul_f32_e32 v71, 0xbfb8aa3b, v71
	v_exp_f32_e32 v68, v68
	v_exp_f32_e32 v69, v69
	v_exp_f32_e32 v70, v70
	v_exp_f32_e32 v71, v71
	v_add_f32_e32 v68, 1.0, v68
	v_add_f32_e32 v69, 1.0, v69
	v_add_f32_e32 v70, 1.0, v70
	v_add_f32_e32 v71, 1.0, v71
	v_rcp_f32_e32 v68, v68
	v_rcp_f32_e32 v69, v69
	v_rcp_f32_e32 v70, v70
	v_rcp_f32_e32 v71, v71
	v_mul_f32_e32 v68, 0xbf1b4598, v68
	v_mul_f32_e32 v69, 0xbf1b4598, v69
	v_mul_f32_e32 v70, 0xbf1b4598, v70
	v_mul_f32_e32 v71, 0xbf1b4598, v71
	v_mul_f32_e32 v68, 0x3fb8aa3b, v68
	v_mul_f32_e32 v69, 0x3fb8aa3b, v69
	v_mul_f32_e32 v70, 0x3fb8aa3b, v70
	v_mul_f32_e32 v71, 0x3fb8aa3b, v71
	v_exp_f32_e32 v68, v68
	v_exp_f32_e32 v69, v69
	v_exp_f32_e32 v70, v70
	v_exp_f32_e32 v71, v71
	s_nop 0
	v_mov_b32_dpp v252, v68 row_ror:8 row_mask:0xf bank_mask:0xf
	v_mov_b32_dpp v253, v69 row_ror:8 row_mask:0xf bank_mask:0xf
	v_mov_b32_dpp v254, v70 row_ror:8 row_mask:0xf bank_mask:0xf
	v_mov_b32_dpp v255, v71 row_ror:8 row_mask:0xf bank_mask:0xf
	v_mov_b32_dpp v68, v72 row_ror:8 row_mask:0xf bank_mask:0x3
	v_mov_b32_dpp v69, v73 row_ror:8 row_mask:0xf bank_mask:0x3
	v_mov_b32_dpp v70, v74 row_ror:8 row_mask:0xf bank_mask:0x3
	v_mov_b32_dpp v71, v75 row_ror:8 row_mask:0xf bank_mask:0x3
	v_mov_b32_dpp v72, v252 quad_perm:[0,1,2,3] row_mask:0xf bank_mask:0xc
; __device__ __forceinline__ void epilogue(const f32x4 (&acc)[2][2][4][2], const Unit& u, LAS unsigned char* lds, int wr, int wc, int fr, int fq) {
;     ...
;                     for (int n = 0; n < 2; ++n) { f32x4 v = acc[ai][bj][m][n];
;                         if (mode >= 5) { v += *(const f32x4*)(bias + col0 + bj * HALF + n * 16);
; #pragma unroll
;                             for (int q = 0; q < 4; ++q) { const float sg = __builtin_amdgcn_rcpf(1.f + __expf(-v[q])); v[q] = mode == 5 ? __expf(-0.6065306597126334f * sg) : sg; } }
;                         *(f32x4*)(rowp + bj * HALF + n * 16) = v; }
	v_mov_b32_dpp v73, v253 quad_perm:[0,1,2,3] row_mask:0xf bank_mask:0xc
	v_mov_b32_dpp v74, v254 quad_perm:[0,1,2,3] row_mask:0xf bank_mask:0xc
	v_mov_b32_dpp v75, v255 quad_perm:[0,1,2,3] row_mask:0xf bank_mask:0xc
	global_store_dwordx4 v[144:145], v[72:75], off offset:512
	global_store_dwordx4 v[142:143], v[68:71], off offset:512
	v_lshl_add_u64 v[144:145], s[2:3], 2, v[144:145]
	v_lshl_add_u64 v[142:143], s[2:3], 2, v[142:143]
	v_lshl_add_u64 v[144:145], s[2:3], 0, v[144:145]
	v_lshl_add_u64 v[142:143], s[2:3], 0, v[142:143]
	v_pk_add_f32 v[66:67], v[66:67], v[238:239]
	v_pk_add_f32 v[64:65], v[64:65], v[236:237]
	v_mul_f32_e32 v66, 0xbfb8aa3b, v66
	v_mul_f32_e32 v64, 0xbfb8aa3b, v64
	v_mul_f32_e32 v65, 0xbfb8aa3b, v65
	v_mul_f32_e32 v67, 0xbfb8aa3b, v67
	v_exp_f32_e32 v64, v64
	v_exp_f32_e32 v65, v65
	v_exp_f32_e32 v66, v66
	v_exp_f32_e32 v67, v67
	v_add_f32_e32 v64, 1.0, v64
	v_add_f32_e32 v65, 1.0, v65
	v_add_f32_e32 v66, 1.0, v66
	v_add_f32_e32 v67, 1.0, v67
	v_rcp_f32_e32 v64, v64
	v_rcp_f32_e32 v65, v65
	v_rcp_f32_e32 v66, v66
	v_rcp_f32_e32 v67, v67
	v_mul_f32_e32 v64, 0xbf1b4598, v64
	v_mul_f32_e32 v65, 0xbf1b4598, v65
	v_mul_f32_e32 v66, 0xbf1b4598, v66
	v_mul_f32_e32 v67, 0xbf1b4598, v67
	v_mul_f32_e32 v64, 0x3fb8aa3b, v64
	v_mul_f32_e32 v65, 0x3fb8aa3b, v65
	v_mul_f32_e32 v66, 0x3fb8aa3b, v66
	v_mul_f32_e32 v67, 0x3fb8aa3b, v67
	v_exp_f32_e32 v64, v64
	v_exp_f32_e32 v65, v65
	v_exp_f32_e32 v66, v66
	v_exp_f32_e32 v67, v67
	v_pk_add_f32 v[62:63], v[62:63], v[242:243]
	v_pk_add_f32 v[60:61], v[60:61], v[240:241]
	v_mul_f32_e32 v62, 0xbfb8aa3b, v62
	v_mul_f32_e32 v60, 0xbfb8aa3b, v60
	v_mul_f32_e32 v61, 0xbfb8aa3b, v61
	v_mul_f32_e32 v63, 0xbfb8aa3b, v63
	v_exp_f32_e32 v60, v60
	v_exp_f32_e32 v61, v61
	v_exp_f32_e32 v62, v62
	v_exp_f32_e32 v63, v63
	v_add_f32_e32 v60, 1.0, v60
	v_add_f32_e32 v61, 1.0, v61
	v_add_f32_e32 v62, 1.0, v62
	v_add_f32_e32 v63, 1.0, v63
	v_rcp_f32_e32 v60, v60
	v_rcp_f32_e32 v61, v61
	v_rcp_f32_e32 v62, v62
	v_rcp_f32_e32 v63, v63
	v_mul_f32_e32 v60, 0xbf1b4598, v60
	v_mul_f32_e32 v61, 0xbf1b4598, v61
	v_mul_f32_e32 v62, 0xbf1b4598, v62
	v_mul_f32_e32 v63, 0xbf1b4598, v63
	v_mul_f32_e32 v60, 0x3fb8aa3b, v60
	v_mul_f32_e32 v61, 0x3fb8aa3b, v61
	v_mul_f32_e32 v62, 0x3fb8aa3b, v62
	v_mul_f32_e32 v63, 0x3fb8aa3b, v63
	v_exp_f32_e32 v60, v60
	v_exp_f32_e32 v61, v61
	v_exp_f32_e32 v62, v62
	v_exp_f32_e32 v63, v63
	s_nop 0
	v_mov_b32_dpp v252, v60 row_ror:8 row_mask:0xf bank_mask:0xf
	v_mov_b32_dpp v253, v61 row_ror:8 row_mask:0xf bank_mask:0xf
	v_mov_b32_dpp v254, v62 row_ror:8 row_mask:0xf bank_mask:0xf
	v_mov_b32_dpp v255, v63 row_ror:8 row_mask:0xf bank_mask:0xf
	v_mov_b32_dpp v60, v64 row_ror:8 row_mask:0xf bank_mask:0x3
	v_mov_b32_dpp v61, v65 row_ror:8 row_mask:0xf bank_mask:0x3
	v_mov_b32_dpp v62, v66 row_ror:8 row_mask:0xf bank_mask:0x3
	v_mov_b32_dpp v63, v67 row_ror:8 row_mask:0xf bank_mask:0x3
	v_mov_b32_dpp v64, v252 quad_perm:[0,1,2,3] row_mask:0xf bank_mask:0xc
	v_mov_b32_dpp v65, v253 quad_perm:[0,1,2,3] row_mask:0xf bank_mask:0xc
	v_mov_b32_dpp v66, v254 quad_perm:[0,1,2,3] row_mask:0xf bank_mask:0xc
	v_mov_b32_dpp v67, v255 quad_perm:[0,1,2,3] row_mask:0xf bank_mask:0xc
	global_store_dwordx4 v[144:145], v[64:67], off
	global_store_dwordx4 v[142:143], v[60:63], off
	v_pk_add_f32 v[58:59], v[58:59], v[246:247]
	v_pk_add_f32 v[56:57], v[56:57], v[244:245]
	v_mul_f32_e32 v58, 0xbfb8aa3b, v58
	v_mul_f32_e32 v56, 0xbfb8aa3b, v56
	v_mul_f32_e32 v57, 0xbfb8aa3b, v57
	v_mul_f32_e32 v59, 0xbfb8aa3b, v59
	v_exp_f32_e32 v56, v56
	v_exp_f32_e32 v57, v57
	v_exp_f32_e32 v58, v58
	v_exp_f32_e32 v59, v59
	v_add_f32_e32 v56, 1.0, v56
	v_add_f32_e32 v57, 1.0, v57
	v_add_f32_e32 v58, 1.0, v58
	v_add_f32_e32 v59, 1.0, v59
	v_rcp_f32_e32 v56, v56
	v_rcp_f32_e32 v57, v57
	v_rcp_f32_e32 v58, v58
	v_rcp_f32_e32 v59, v59
	v_mul_f32_e32 v56, 0xbf1b4598, v56
	v_mul_f32_e32 v57, 0xbf1b4598, v57
	v_mul_f32_e32 v58, 0xbf1b4598, v58
	v_mul_f32_e32 v59, 0xbf1b4598, v59
	v_mul_f32_e32 v56, 0x3fb8aa3b, v56
	v_mul_f32_e32 v57, 0x3fb8aa3b, v57
	v_mul_f32_e32 v58, 0x3fb8aa3b, v58
	v_mul_f32_e32 v59, 0x3fb8aa3b, v59
	v_exp_f32_e32 v56, v56
	v_exp_f32_e32 v57, v57
	v_exp_f32_e32 v58, v58
	v_exp_f32_e32 v59, v59
	v_pk_add_f32 v[54:55], v[54:55], v[250:251]
	v_pk_add_f32 v[52:53], v[52:53], v[248:249]
	v_mul_f32_e32 v54, 0xbfb8aa3b, v54
	v_mul_f32_e32 v52, 0xbfb8aa3b, v52
	v_mul_f32_e32 v53, 0xbfb8aa3b, v53
	v_mul_f32_e32 v55, 0xbfb8aa3b, v55
	v_exp_f32_e32 v52, v52
	v_exp_f32_e32 v53, v53
	v_exp_f32_e32 v54, v54
	v_exp_f32_e32 v55, v55
	v_add_f32_e32 v52, 1.0, v52
	v_add_f32_e32 v53, 1.0, v53
	v_add_f32_e32 v54, 1.0, v54
	v_add_f32_e32 v55, 1.0, v55
	v_rcp_f32_e32 v52, v52
	v_rcp_f32_e32 v53, v53
	v_rcp_f32_e32 v54, v54
	v_rcp_f32_e32 v55, v55
	v_mul_f32_e32 v52, 0xbf1b4598, v52
	v_mul_f32_e32 v53, 0xbf1b4598, v53
	v_mul_f32_e32 v54, 0xbf1b4598, v54
	v_mul_f32_e32 v55, 0xbf1b4598, v55
	v_mul_f32_e32 v52, 0x3fb8aa3b, v52
	v_mul_f32_e32 v53, 0x3fb8aa3b, v53
	v_mul_f32_e32 v54, 0x3fb8aa3b, v54
	v_mul_f32_e32 v55, 0x3fb8aa3b, v55
	v_exp_f32_e32 v52, v52
	v_exp_f32_e32 v53, v53
	v_exp_f32_e32 v54, v54
	v_exp_f32_e32 v55, v55
	s_nop 0
	v_mov_b32_dpp v252, v52 row_ror:8 row_mask:0xf bank_mask:0xf
	v_mov_b32_dpp v253, v53 row_ror:8 row_mask:0xf bank_mask:0xf
	v_mov_b32_dpp v254, v54 row_ror:8 row_mask:0xf bank_mask:0xf
	v_mov_b32_dpp v255, v55 row_ror:8 row_mask:0xf bank_mask:0xf
	v_mov_b32_dpp v52, v56 row_ror:8 row_mask:0xf bank_mask:0x3
	v_mov_b32_dpp v53, v57 row_ror:8 row_mask:0xf bank_mask:0x3
	v_mov_b32_dpp v54, v58 row_ror:8 row_mask:0xf bank_mask:0x3
	v_mov_b32_dpp v55, v59 row_ror:8 row_mask:0xf bank_mask:0x3
; __device__ __forceinline__ void epilogue(const f32x4 (&acc)[2][2][4][2], const Unit& u, LAS unsigned char* lds, int wr, int wc, int fr, int fq) {
;     ...
;                     for (int n = 0; n < 2; ++n) { f32x4 v = acc[ai][bj][m][n];
;                         if (mode >= 5) { v += *(const f32x4*)(bias + col0 + bj * HALF + n * 16);
; #pragma unroll
;                             for (int q = 0; q < 4; ++q) { const float sg = __builtin_amdgcn_rcpf(1.f + __expf(-v[q])); v[q] = mode == 5 ? __expf(-0.6065306597126334f * sg) : sg; } }
;                         *(f32x4*)(rowp + bj * HALF + n * 16) = v; }
	v_mov_b32_dpp v56, v252 quad_perm:[0,1,2,3] row_mask:0xf bank_mask:0xc
	v_mov_b32_dpp v57, v253 quad_perm:[0,1,2,3] row_mask:0xf bank_mask:0xc
	v_mov_b32_dpp v58, v254 quad_perm:[0,1,2,3] row_mask:0xf bank_mask:0xc
	v_mov_b32_dpp v59, v255 quad_perm:[0,1,2,3] row_mask:0xf bank_mask:0xc
	global_store_dwordx4 v[144:145], v[56:59], off offset:512
	global_store_dwordx4 v[142:143], v[52:55], off offset:512
	v_lshl_add_u64 v[144:145], s[2:3], 0, v[144:145]
	v_lshl_add_u64 v[142:143], s[2:3], 0, v[142:143]
	v_pk_add_f32 v[50:51], v[50:51], v[238:239]
	v_pk_add_f32 v[48:49], v[48:49], v[236:237]
	v_mul_f32_e32 v50, 0xbfb8aa3b, v50
	v_mul_f32_e32 v48, 0xbfb8aa3b, v48
	v_mul_f32_e32 v49, 0xbfb8aa3b, v49
	v_mul_f32_e32 v51, 0xbfb8aa3b, v51
	v_exp_f32_e32 v48, v48
	v_exp_f32_e32 v49, v49
	v_exp_f32_e32 v50, v50
	v_exp_f32_e32 v51, v51
	v_add_f32_e32 v48, 1.0, v48
	v_add_f32_e32 v49, 1.0, v49
	v_add_f32_e32 v50, 1.0, v50
	v_add_f32_e32 v51, 1.0, v51
	v_rcp_f32_e32 v48, v48
	v_rcp_f32_e32 v49, v49
	v_rcp_f32_e32 v50, v50
	v_rcp_f32_e32 v51, v51
	v_mul_f32_e32 v48, 0xbf1b4598, v48
	v_mul_f32_e32 v49, 0xbf1b4598, v49
	v_mul_f32_e32 v50, 0xbf1b4598, v50
	v_mul_f32_e32 v51, 0xbf1b4598, v51
	v_mul_f32_e32 v48, 0x3fb8aa3b, v48
	v_mul_f32_e32 v49, 0x3fb8aa3b, v49
	v_mul_f32_e32 v50, 0x3fb8aa3b, v50
	v_mul_f32_e32 v51, 0x3fb8aa3b, v51
	v_exp_f32_e32 v48, v48
	v_exp_f32_e32 v49, v49
	v_exp_f32_e32 v50, v50
	v_exp_f32_e32 v51, v51
	v_pk_add_f32 v[46:47], v[46:47], v[242:243]
	v_pk_add_f32 v[44:45], v[44:45], v[240:241]
	v_mul_f32_e32 v46, 0xbfb8aa3b, v46
	v_mul_f32_e32 v44, 0xbfb8aa3b, v44
	v_mul_f32_e32 v45, 0xbfb8aa3b, v45
	v_mul_f32_e32 v47, 0xbfb8aa3b, v47
	v_exp_f32_e32 v44, v44
	v_exp_f32_e32 v45, v45
	v_exp_f32_e32 v46, v46
	v_exp_f32_e32 v47, v47
	v_add_f32_e32 v44, 1.0, v44
	v_add_f32_e32 v45, 1.0, v45
	v_add_f32_e32 v46, 1.0, v46
	v_add_f32_e32 v47, 1.0, v47
	v_rcp_f32_e32 v44, v44
	v_rcp_f32_e32 v45, v45
	v_rcp_f32_e32 v46, v46
	v_rcp_f32_e32 v47, v47
	v_mul_f32_e32 v44, 0xbf1b4598, v44
	v_mul_f32_e32 v45, 0xbf1b4598, v45
	v_mul_f32_e32 v46, 0xbf1b4598, v46
	v_mul_f32_e32 v47, 0xbf1b4598, v47
	v_mul_f32_e32 v44, 0x3fb8aa3b, v44
	v_mul_f32_e32 v45, 0x3fb8aa3b, v45
	v_mul_f32_e32 v46, 0x3fb8aa3b, v46
	v_mul_f32_e32 v47, 0x3fb8aa3b, v47
	v_exp_f32_e32 v44, v44
	v_exp_f32_e32 v45, v45
	v_exp_f32_e32 v46, v46
	v_exp_f32_e32 v47, v47
	s_nop 0
	v_mov_b32_dpp v252, v44 row_ror:8 row_mask:0xf bank_mask:0xf
	v_mov_b32_dpp v253, v45 row_ror:8 row_mask:0xf bank_mask:0xf
	v_mov_b32_dpp v254, v46 row_ror:8 row_mask:0xf bank_mask:0xf
	v_mov_b32_dpp v255, v47 row_ror:8 row_mask:0xf bank_mask:0xf
	v_mov_b32_dpp v44, v48 row_ror:8 row_mask:0xf bank_mask:0x3
	v_mov_b32_dpp v45, v49 row_ror:8 row_mask:0xf bank_mask:0x3
	v_mov_b32_dpp v46, v50 row_ror:8 row_mask:0xf bank_mask:0x3
	v_mov_b32_dpp v47, v51 row_ror:8 row_mask:0xf bank_mask:0x3
	v_mov_b32_dpp v48, v252 quad_perm:[0,1,2,3] row_mask:0xf bank_mask:0xc
	v_mov_b32_dpp v49, v253 quad_perm:[0,1,2,3] row_mask:0xf bank_mask:0xc
	v_mov_b32_dpp v50, v254 quad_perm:[0,1,2,3] row_mask:0xf bank_mask:0xc
	v_mov_b32_dpp v51, v255 quad_perm:[0,1,2,3] row_mask:0xf bank_mask:0xc
	global_store_dwordx4 v[144:145], v[48:51], off
	global_store_dwordx4 v[142:143], v[44:47], off
	v_pk_add_f32 v[42:43], v[42:43], v[246:247]
	v_pk_add_f32 v[40:41], v[40:41], v[244:245]
	v_mul_f32_e32 v42, 0xbfb8aa3b, v42
	v_mul_f32_e32 v40, 0xbfb8aa3b, v40
	v_mul_f32_e32 v41, 0xbfb8aa3b, v41
	v_mul_f32_e32 v43, 0xbfb8aa3b, v43
	v_exp_f32_e32 v40, v40
	v_exp_f32_e32 v41, v41
	v_exp_f32_e32 v42, v42
	v_exp_f32_e32 v43, v43
	v_add_f32_e32 v40, 1.0, v40
	v_add_f32_e32 v41, 1.0, v41
	v_add_f32_e32 v42, 1.0, v42
	v_add_f32_e32 v43, 1.0, v43
	v_rcp_f32_e32 v40, v40
	v_rcp_f32_e32 v41, v41
	v_rcp_f32_e32 v42, v42
	v_rcp_f32_e32 v43, v43
	v_mul_f32_e32 v40, 0xbf1b4598, v40
	v_mul_f32_e32 v41, 0xbf1b4598, v41
	v_mul_f32_e32 v42, 0xbf1b4598, v42
	v_mul_f32_e32 v43, 0xbf1b4598, v43
	v_mul_f32_e32 v40, 0x3fb8aa3b, v40
	v_mul_f32_e32 v41, 0x3fb8aa3b, v41
	v_mul_f32_e32 v42, 0x3fb8aa3b, v42
	v_mul_f32_e32 v43, 0x3fb8aa3b, v43
	v_exp_f32_e32 v40, v40
	v_exp_f32_e32 v41, v41
	v_exp_f32_e32 v42, v42
	v_exp_f32_e32 v43, v43
	v_pk_add_f32 v[38:39], v[38:39], v[250:251]
	v_pk_add_f32 v[36:37], v[36:37], v[248:249]
	v_mul_f32_e32 v38, 0xbfb8aa3b, v38
	v_mul_f32_e32 v36, 0xbfb8aa3b, v36
	v_mul_f32_e32 v37, 0xbfb8aa3b, v37
	v_mul_f32_e32 v39, 0xbfb8aa3b, v39
	v_exp_f32_e32 v36, v36
	v_exp_f32_e32 v37, v37
	v_exp_f32_e32 v38, v38
	v_exp_f32_e32 v39, v39
	v_add_f32_e32 v36, 1.0, v36
	v_add_f32_e32 v37, 1.0, v37
	v_add_f32_e32 v38, 1.0, v38
	v_add_f32_e32 v39, 1.0, v39
	v_rcp_f32_e32 v36, v36
	v_rcp_f32_e32 v37, v37
	v_rcp_f32_e32 v38, v38
	v_rcp_f32_e32 v39, v39
	v_mul_f32_e32 v36, 0xbf1b4598, v36
	v_mul_f32_e32 v37, 0xbf1b4598, v37
	v_mul_f32_e32 v38, 0xbf1b4598, v38
	v_mul_f32_e32 v39, 0xbf1b4598, v39
	v_mul_f32_e32 v36, 0x3fb8aa3b, v36
	v_mul_f32_e32 v37, 0x3fb8aa3b, v37
	v_mul_f32_e32 v38, 0x3fb8aa3b, v38
	v_mul_f32_e32 v39, 0x3fb8aa3b, v39
	v_exp_f32_e32 v36, v36
	v_exp_f32_e32 v37, v37
	v_exp_f32_e32 v38, v38
	v_exp_f32_e32 v39, v39
	s_nop 0
	v_mov_b32_dpp v252, v36 row_ror:8 row_mask:0xf bank_mask:0xf
	v_mov_b32_dpp v253, v37 row_ror:8 row_mask:0xf bank_mask:0xf
	v_mov_b32_dpp v254, v38 row_ror:8 row_mask:0xf bank_mask:0xf
	v_mov_b32_dpp v255, v39 row_ror:8 row_mask:0xf bank_mask:0xf
	v_mov_b32_dpp v36, v40 row_ror:8 row_mask:0xf bank_mask:0x3
	v_mov_b32_dpp v37, v41 row_ror:8 row_mask:0xf bank_mask:0x3
	v_mov_b32_dpp v38, v42 row_ror:8 row_mask:0xf bank_mask:0x3
	v_mov_b32_dpp v39, v43 row_ror:8 row_mask:0xf bank_mask:0x3
	v_mov_b32_dpp v40, v252 quad_perm:[0,1,2,3] row_mask:0xf bank_mask:0xc
; __device__ __forceinline__ void epilogue(const f32x4 (&acc)[2][2][4][2], const Unit& u, LAS unsigned char* lds, int wr, int wc, int fr, int fq) {
;     ...
;                     for (int n = 0; n < 2; ++n) { f32x4 v = acc[ai][bj][m][n];
;                         if (mode >= 5) { v += *(const f32x4*)(bias + col0 + bj * HALF + n * 16);
; #pragma unroll
;                             for (int q = 0; q < 4; ++q) { const float sg = __builtin_amdgcn_rcpf(1.f + __expf(-v[q])); v[q] = mode == 5 ? __expf(-0.6065306597126334f * sg) : sg; } }
;                         *(f32x4*)(rowp + bj * HALF + n * 16) = v; }
	v_mov_b32_dpp v41, v253 quad_perm:[0,1,2,3] row_mask:0xf bank_mask:0xc
	v_mov_b32_dpp v42, v254 quad_perm:[0,1,2,3] row_mask:0xf bank_mask:0xc
	v_mov_b32_dpp v43, v255 quad_perm:[0,1,2,3] row_mask:0xf bank_mask:0xc
	global_store_dwordx4 v[144:145], v[40:43], off offset:512
	global_store_dwordx4 v[142:143], v[36:39], off offset:512
	v_lshl_add_u64 v[144:145], s[2:3], 0, v[144:145]
	v_lshl_add_u64 v[142:143], s[2:3], 0, v[142:143]
	v_pk_add_f32 v[34:35], v[34:35], v[238:239]
	v_pk_add_f32 v[32:33], v[32:33], v[236:237]
	v_mul_f32_e32 v34, 0xbfb8aa3b, v34
	v_mul_f32_e32 v32, 0xbfb8aa3b, v32
	v_mul_f32_e32 v33, 0xbfb8aa3b, v33
	v_mul_f32_e32 v35, 0xbfb8aa3b, v35
	v_exp_f32_e32 v32, v32
	v_exp_f32_e32 v33, v33
	v_exp_f32_e32 v34, v34
	v_exp_f32_e32 v35, v35
	v_add_f32_e32 v32, 1.0, v32
	v_add_f32_e32 v33, 1.0, v33
	v_add_f32_e32 v34, 1.0, v34
	v_add_f32_e32 v35, 1.0, v35
	v_rcp_f32_e32 v32, v32
	v_rcp_f32_e32 v33, v33
	v_rcp_f32_e32 v34, v34
	v_rcp_f32_e32 v35, v35
	v_mul_f32_e32 v32, 0xbf1b4598, v32
	v_mul_f32_e32 v33, 0xbf1b4598, v33
	v_mul_f32_e32 v34, 0xbf1b4598, v34
	v_mul_f32_e32 v35, 0xbf1b4598, v35
	v_mul_f32_e32 v32, 0x3fb8aa3b, v32
	v_mul_f32_e32 v33, 0x3fb8aa3b, v33
	v_mul_f32_e32 v34, 0x3fb8aa3b, v34
	v_mul_f32_e32 v35, 0x3fb8aa3b, v35
	v_exp_f32_e32 v32, v32
	v_exp_f32_e32 v33, v33
	v_exp_f32_e32 v34, v34
	v_exp_f32_e32 v35, v35
	v_pk_add_f32 v[30:31], v[30:31], v[242:243]
	v_pk_add_f32 v[28:29], v[28:29], v[240:241]
	v_mul_f32_e32 v30, 0xbfb8aa3b, v30
	v_mul_f32_e32 v28, 0xbfb8aa3b, v28
	v_mul_f32_e32 v29, 0xbfb8aa3b, v29
	v_mul_f32_e32 v31, 0xbfb8aa3b, v31
	v_exp_f32_e32 v28, v28
	v_exp_f32_e32 v29, v29
	v_exp_f32_e32 v30, v30
	v_exp_f32_e32 v31, v31
	v_add_f32_e32 v28, 1.0, v28
	v_add_f32_e32 v29, 1.0, v29
	v_add_f32_e32 v30, 1.0, v30
	v_add_f32_e32 v31, 1.0, v31
	v_rcp_f32_e32 v28, v28
	v_rcp_f32_e32 v29, v29
	v_rcp_f32_e32 v30, v30
	v_rcp_f32_e32 v31, v31
	v_mul_f32_e32 v28, 0xbf1b4598, v28
	v_mul_f32_e32 v29, 0xbf1b4598, v29
	v_mul_f32_e32 v30, 0xbf1b4598, v30
	v_mul_f32_e32 v31, 0xbf1b4598, v31
	v_mul_f32_e32 v28, 0x3fb8aa3b, v28
	v_mul_f32_e32 v29, 0x3fb8aa3b, v29
	v_mul_f32_e32 v30, 0x3fb8aa3b, v30
	v_mul_f32_e32 v31, 0x3fb8aa3b, v31
	v_exp_f32_e32 v28, v28
	v_exp_f32_e32 v29, v29
	v_exp_f32_e32 v30, v30
	v_exp_f32_e32 v31, v31
	s_nop 0
	v_mov_b32_dpp v252, v28 row_ror:8 row_mask:0xf bank_mask:0xf
	v_mov_b32_dpp v253, v29 row_ror:8 row_mask:0xf bank_mask:0xf
	v_mov_b32_dpp v254, v30 row_ror:8 row_mask:0xf bank_mask:0xf
	v_mov_b32_dpp v255, v31 row_ror:8 row_mask:0xf bank_mask:0xf
	v_mov_b32_dpp v28, v32 row_ror:8 row_mask:0xf bank_mask:0x3
	v_mov_b32_dpp v29, v33 row_ror:8 row_mask:0xf bank_mask:0x3
	v_mov_b32_dpp v30, v34 row_ror:8 row_mask:0xf bank_mask:0x3
	v_mov_b32_dpp v31, v35 row_ror:8 row_mask:0xf bank_mask:0x3
	v_mov_b32_dpp v32, v252 quad_perm:[0,1,2,3] row_mask:0xf bank_mask:0xc
	v_mov_b32_dpp v33, v253 quad_perm:[0,1,2,3] row_mask:0xf bank_mask:0xc
	v_mov_b32_dpp v34, v254 quad_perm:[0,1,2,3] row_mask:0xf bank_mask:0xc
	v_mov_b32_dpp v35, v255 quad_perm:[0,1,2,3] row_mask:0xf bank_mask:0xc
	global_store_dwordx4 v[144:145], v[32:35], off
	global_store_dwordx4 v[142:143], v[28:31], off
	v_pk_add_f32 v[26:27], v[26:27], v[246:247]
	v_pk_add_f32 v[24:25], v[24:25], v[244:245]
	v_mul_f32_e32 v26, 0xbfb8aa3b, v26
	v_mul_f32_e32 v24, 0xbfb8aa3b, v24
	v_mul_f32_e32 v25, 0xbfb8aa3b, v25
	v_mul_f32_e32 v27, 0xbfb8aa3b, v27
	v_exp_f32_e32 v24, v24
	v_exp_f32_e32 v25, v25
	v_exp_f32_e32 v26, v26
	v_exp_f32_e32 v27, v27
	v_add_f32_e32 v24, 1.0, v24
	v_add_f32_e32 v25, 1.0, v25
	v_add_f32_e32 v26, 1.0, v26
	v_add_f32_e32 v27, 1.0, v27
	v_rcp_f32_e32 v24, v24
	v_rcp_f32_e32 v25, v25
	v_rcp_f32_e32 v26, v26
	v_rcp_f32_e32 v27, v27
	v_mul_f32_e32 v24, 0xbf1b4598, v24
	v_mul_f32_e32 v25, 0xbf1b4598, v25
	v_mul_f32_e32 v26, 0xbf1b4598, v26
	v_mul_f32_e32 v27, 0xbf1b4598, v27
	v_mul_f32_e32 v24, 0x3fb8aa3b, v24
	v_mul_f32_e32 v25, 0x3fb8aa3b, v25
	v_mul_f32_e32 v26, 0x3fb8aa3b, v26
	v_mul_f32_e32 v27, 0x3fb8aa3b, v27
	v_exp_f32_e32 v24, v24
	v_exp_f32_e32 v25, v25
	v_exp_f32_e32 v26, v26
	v_exp_f32_e32 v27, v27
	v_pk_add_f32 v[22:23], v[22:23], v[250:251]
	v_pk_add_f32 v[20:21], v[20:21], v[248:249]
	v_mul_f32_e32 v22, 0xbfb8aa3b, v22
	v_mul_f32_e32 v20, 0xbfb8aa3b, v20
	v_mul_f32_e32 v21, 0xbfb8aa3b, v21
	v_mul_f32_e32 v23, 0xbfb8aa3b, v23
	v_exp_f32_e32 v20, v20
	v_exp_f32_e32 v21, v21
	v_exp_f32_e32 v22, v22
	v_exp_f32_e32 v23, v23
	v_add_f32_e32 v20, 1.0, v20
	v_add_f32_e32 v21, 1.0, v21
	v_add_f32_e32 v22, 1.0, v22
	v_add_f32_e32 v23, 1.0, v23
	v_rcp_f32_e32 v20, v20
	v_rcp_f32_e32 v21, v21
	v_rcp_f32_e32 v22, v22
	v_rcp_f32_e32 v23, v23
	v_mul_f32_e32 v20, 0xbf1b4598, v20
	v_mul_f32_e32 v21, 0xbf1b4598, v21
	v_mul_f32_e32 v22, 0xbf1b4598, v22
	v_mul_f32_e32 v23, 0xbf1b4598, v23
	v_mul_f32_e32 v20, 0x3fb8aa3b, v20
	v_mul_f32_e32 v21, 0x3fb8aa3b, v21
	v_mul_f32_e32 v22, 0x3fb8aa3b, v22
	v_mul_f32_e32 v23, 0x3fb8aa3b, v23
	v_exp_f32_e32 v20, v20
	v_exp_f32_e32 v21, v21
	v_exp_f32_e32 v22, v22
	v_exp_f32_e32 v23, v23
	s_nop 0
	v_mov_b32_dpp v252, v20 row_ror:8 row_mask:0xf bank_mask:0xf
	v_mov_b32_dpp v253, v21 row_ror:8 row_mask:0xf bank_mask:0xf
	v_mov_b32_dpp v254, v22 row_ror:8 row_mask:0xf bank_mask:0xf
	v_mov_b32_dpp v255, v23 row_ror:8 row_mask:0xf bank_mask:0xf
	v_mov_b32_dpp v20, v24 row_ror:8 row_mask:0xf bank_mask:0x3
	v_mov_b32_dpp v21, v25 row_ror:8 row_mask:0xf bank_mask:0x3
	v_mov_b32_dpp v22, v26 row_ror:8 row_mask:0xf bank_mask:0x3
	v_mov_b32_dpp v23, v27 row_ror:8 row_mask:0xf bank_mask:0x3
	v_mov_b32_dpp v24, v252 quad_perm:[0,1,2,3] row_mask:0xf bank_mask:0xc
	v_mov_b32_dpp v25, v253 quad_perm:[0,1,2,3] row_mask:0xf bank_mask:0xc
; __device__ __forceinline__ void epilogue(const f32x4 (&acc)[2][2][4][2], const Unit& u, LAS unsigned char* lds, int wr, int wc, int fr, int fq) {
;     ...
;                     for (int n = 0; n < 2; ++n) { f32x4 v = acc[ai][bj][m][n];
;                         if (mode >= 5) { v += *(const f32x4*)(bias + col0 + bj * HALF + n * 16);
; #pragma unroll
;                             for (int q = 0; q < 4; ++q) { const float sg = __builtin_amdgcn_rcpf(1.f + __expf(-v[q])); v[q] = mode == 5 ? __expf(-0.6065306597126334f * sg) : sg; } }
;                         *(f32x4*)(rowp + bj * HALF + n * 16) = v; }
	v_mov_b32_dpp v26, v254 quad_perm:[0,1,2,3] row_mask:0xf bank_mask:0xc
	v_mov_b32_dpp v27, v255 quad_perm:[0,1,2,3] row_mask:0xf bank_mask:0xc
	global_store_dwordx4 v[144:145], v[24:27], off offset:512
	global_store_dwordx4 v[142:143], v[20:23], off offset:512
	v_lshl_add_u64 v[144:145], s[2:3], 0, v[144:145]
	v_lshl_add_u64 v[142:143], s[2:3], 0, v[142:143]
	v_pk_add_f32 v[18:19], v[18:19], v[238:239]
	v_pk_add_f32 v[16:17], v[16:17], v[236:237]
	v_mul_f32_e32 v18, 0xbfb8aa3b, v18
	v_mul_f32_e32 v16, 0xbfb8aa3b, v16
	v_mul_f32_e32 v17, 0xbfb8aa3b, v17
	v_mul_f32_e32 v19, 0xbfb8aa3b, v19
	v_exp_f32_e32 v16, v16
	v_exp_f32_e32 v17, v17
	v_exp_f32_e32 v18, v18
	v_exp_f32_e32 v19, v19
	v_add_f32_e32 v16, 1.0, v16
	v_add_f32_e32 v17, 1.0, v17
	v_add_f32_e32 v18, 1.0, v18
	v_add_f32_e32 v19, 1.0, v19
	v_rcp_f32_e32 v16, v16
	v_rcp_f32_e32 v17, v17
	v_rcp_f32_e32 v18, v18
	v_rcp_f32_e32 v19, v19
	v_mul_f32_e32 v16, 0xbf1b4598, v16
	v_mul_f32_e32 v17, 0xbf1b4598, v17
	v_mul_f32_e32 v18, 0xbf1b4598, v18
	v_mul_f32_e32 v19, 0xbf1b4598, v19
	v_mul_f32_e32 v16, 0x3fb8aa3b, v16
	v_mul_f32_e32 v17, 0x3fb8aa3b, v17
	v_mul_f32_e32 v18, 0x3fb8aa3b, v18
	v_mul_f32_e32 v19, 0x3fb8aa3b, v19
	v_exp_f32_e32 v16, v16
	v_exp_f32_e32 v17, v17
	v_exp_f32_e32 v18, v18
	v_exp_f32_e32 v19, v19
	v_pk_add_f32 v[14:15], v[14:15], v[242:243]
	v_pk_add_f32 v[12:13], v[12:13], v[240:241]
	v_mul_f32_e32 v14, 0xbfb8aa3b, v14
	v_mul_f32_e32 v12, 0xbfb8aa3b, v12
	v_mul_f32_e32 v13, 0xbfb8aa3b, v13
	v_mul_f32_e32 v15, 0xbfb8aa3b, v15
	v_exp_f32_e32 v12, v12
	v_exp_f32_e32 v13, v13
	v_exp_f32_e32 v14, v14
	v_exp_f32_e32 v15, v15
	v_add_f32_e32 v12, 1.0, v12
	v_add_f32_e32 v13, 1.0, v13
	v_add_f32_e32 v14, 1.0, v14
	v_add_f32_e32 v15, 1.0, v15
	v_rcp_f32_e32 v12, v12
	v_rcp_f32_e32 v13, v13
	v_rcp_f32_e32 v14, v14
	v_rcp_f32_e32 v15, v15
	v_mul_f32_e32 v12, 0xbf1b4598, v12
	v_mul_f32_e32 v13, 0xbf1b4598, v13
	v_mul_f32_e32 v14, 0xbf1b4598, v14
	v_mul_f32_e32 v15, 0xbf1b4598, v15
	v_mul_f32_e32 v12, 0x3fb8aa3b, v12
	v_mul_f32_e32 v13, 0x3fb8aa3b, v13
	v_mul_f32_e32 v14, 0x3fb8aa3b, v14
	v_mul_f32_e32 v15, 0x3fb8aa3b, v15
	v_exp_f32_e32 v12, v12
	v_exp_f32_e32 v13, v13
	v_exp_f32_e32 v14, v14
	v_exp_f32_e32 v15, v15
	s_nop 0
	v_mov_b32_dpp v252, v12 row_ror:8 row_mask:0xf bank_mask:0xf
	v_mov_b32_dpp v253, v13 row_ror:8 row_mask:0xf bank_mask:0xf
	v_mov_b32_dpp v254, v14 row_ror:8 row_mask:0xf bank_mask:0xf
	v_mov_b32_dpp v255, v15 row_ror:8 row_mask:0xf bank_mask:0xf
	v_mov_b32_dpp v12, v16 row_ror:8 row_mask:0xf bank_mask:0x3
	v_mov_b32_dpp v13, v17 row_ror:8 row_mask:0xf bank_mask:0x3
	v_mov_b32_dpp v14, v18 row_ror:8 row_mask:0xf bank_mask:0x3
	v_mov_b32_dpp v15, v19 row_ror:8 row_mask:0xf bank_mask:0x3
	v_mov_b32_dpp v16, v252 quad_perm:[0,1,2,3] row_mask:0xf bank_mask:0xc
	v_mov_b32_dpp v17, v253 quad_perm:[0,1,2,3] row_mask:0xf bank_mask:0xc
	v_mov_b32_dpp v18, v254 quad_perm:[0,1,2,3] row_mask:0xf bank_mask:0xc
	v_mov_b32_dpp v19, v255 quad_perm:[0,1,2,3] row_mask:0xf bank_mask:0xc
	global_store_dwordx4 v[144:145], v[16:19], off
	global_store_dwordx4 v[142:143], v[12:15], off
	v_pk_add_f32 v[10:11], v[10:11], v[246:247]
	v_pk_add_f32 v[8:9], v[8:9], v[244:245]
	v_mul_f32_e32 v10, 0xbfb8aa3b, v10
	v_mul_f32_e32 v8, 0xbfb8aa3b, v8
	v_mul_f32_e32 v9, 0xbfb8aa3b, v9
	v_mul_f32_e32 v11, 0xbfb8aa3b, v11
	v_exp_f32_e32 v8, v8
	v_exp_f32_e32 v9, v9
	v_exp_f32_e32 v10, v10
	v_exp_f32_e32 v11, v11
	v_add_f32_e32 v8, 1.0, v8
	v_add_f32_e32 v9, 1.0, v9
	v_add_f32_e32 v10, 1.0, v10
	v_add_f32_e32 v11, 1.0, v11
	v_rcp_f32_e32 v8, v8
	v_rcp_f32_e32 v9, v9
	v_rcp_f32_e32 v10, v10
	v_rcp_f32_e32 v11, v11
	v_mul_f32_e32 v8, 0xbf1b4598, v8
	v_mul_f32_e32 v9, 0xbf1b4598, v9
	v_mul_f32_e32 v10, 0xbf1b4598, v10
	v_mul_f32_e32 v11, 0xbf1b4598, v11
	v_mul_f32_e32 v8, 0x3fb8aa3b, v8
	v_mul_f32_e32 v9, 0x3fb8aa3b, v9
	v_mul_f32_e32 v10, 0x3fb8aa3b, v10
	v_mul_f32_e32 v11, 0x3fb8aa3b, v11
	v_exp_f32_e32 v8, v8
	v_exp_f32_e32 v9, v9
	v_exp_f32_e32 v10, v10
	v_exp_f32_e32 v11, v11
	v_pk_add_f32 v[6:7], v[6:7], v[250:251]
	v_pk_add_f32 v[4:5], v[4:5], v[248:249]
	v_mul_f32_e32 v6, 0xbfb8aa3b, v6
	v_mul_f32_e32 v4, 0xbfb8aa3b, v4
	v_mul_f32_e32 v5, 0xbfb8aa3b, v5
	v_mul_f32_e32 v7, 0xbfb8aa3b, v7
	v_exp_f32_e32 v4, v4
	v_exp_f32_e32 v5, v5
	v_exp_f32_e32 v6, v6
	v_exp_f32_e32 v7, v7
	v_add_f32_e32 v4, 1.0, v4
	v_add_f32_e32 v5, 1.0, v5
	v_add_f32_e32 v6, 1.0, v6
	v_add_f32_e32 v7, 1.0, v7
	v_rcp_f32_e32 v4, v4
	v_rcp_f32_e32 v5, v5
	v_rcp_f32_e32 v6, v6
	v_rcp_f32_e32 v7, v7
	v_mul_f32_e32 v4, 0xbf1b4598, v4
	v_mul_f32_e32 v5, 0xbf1b4598, v5
	v_mul_f32_e32 v6, 0xbf1b4598, v6
	v_mul_f32_e32 v7, 0xbf1b4598, v7
	v_mul_f32_e32 v4, 0x3fb8aa3b, v4
	v_mul_f32_e32 v5, 0x3fb8aa3b, v5
	v_mul_f32_e32 v6, 0x3fb8aa3b, v6
	v_mul_f32_e32 v7, 0x3fb8aa3b, v7
	v_exp_f32_e32 v4, v4
	v_exp_f32_e32 v5, v5
	v_exp_f32_e32 v6, v6
	v_exp_f32_e32 v7, v7
	s_nop 0
	v_mov_b32_dpp v252, v4 row_ror:8 row_mask:0xf bank_mask:0xf
	v_mov_b32_dpp v253, v5 row_ror:8 row_mask:0xf bank_mask:0xf
	v_mov_b32_dpp v254, v6 row_ror:8 row_mask:0xf bank_mask:0xf
	v_mov_b32_dpp v255, v7 row_ror:8 row_mask:0xf bank_mask:0xf
	v_mov_b32_dpp v4, v8 row_ror:8 row_mask:0xf bank_mask:0x3
	v_mov_b32_dpp v5, v9 row_ror:8 row_mask:0xf bank_mask:0x3
	v_mov_b32_dpp v6, v10 row_ror:8 row_mask:0xf bank_mask:0x3
	v_mov_b32_dpp v7, v11 row_ror:8 row_mask:0xf bank_mask:0x3
	v_mov_b32_dpp v8, v252 quad_perm:[0,1,2,3] row_mask:0xf bank_mask:0xc
	v_mov_b32_dpp v9, v253 quad_perm:[0,1,2,3] row_mask:0xf bank_mask:0xc
	v_mov_b32_dpp v10, v254 quad_perm:[0,1,2,3] row_mask:0xf bank_mask:0xc
	v_mov_b32_dpp v11, v255 quad_perm:[0,1,2,3] row_mask:0xf bank_mask:0xc
	global_store_dwordx4 v[144:145], v[8:11], off offset:512
	global_store_dwordx4 v[142:143], v[4:7], off offset:512
	s_branch .LBB0_1310

; #define LAS __attribute__((address_space(3)))
; __global__ void __launch_bounds__(512, 2) mega_fwd(Params p) {
;     extern __shared__ __attribute__((aligned(16))) unsigned char lds_raw[];
;     LAS unsigned char* lds = (LAS unsigned char*)lds_raw;
;     cg::grid_group grid = cg::this_grid();
	.amdhsa_kernel _Z8mega_fwd6Params
		.amdhsa_group_segment_fixed_size 0
		.amdhsa_private_segment_fixed_size 0
		.amdhsa_kernarg_size 592
		.amdhsa_user_sgpr_count 2
		.amdhsa_user_sgpr_dispatch_ptr 0
		.amdhsa_user_sgpr_queue_ptr 0
		.amdhsa_user_sgpr_kernarg_segment_ptr 1
		.amdhsa_user_sgpr_dispatch_id 0
		.amdhsa_user_sgpr_kernarg_preload_length 0
		.amdhsa_user_sgpr_kernarg_preload_offset 0
		.amdhsa_user_sgpr_private_segment_size 0
		.amdhsa_uses_dynamic_stack 0
		.amdhsa_enable_private_segment 0
		.amdhsa_system_sgpr_workgroup_id_x 1
		.amdhsa_system_sgpr_workgroup_id_y 0
		.amdhsa_system_sgpr_workgroup_id_z 0
		.amdhsa_system_sgpr_workgroup_info 0
		.amdhsa_system_vgpr_workitem_id 2
		.amdhsa_next_free_vgpr 256
		.amdhsa_next_free_sgpr 102
		.amdhsa_accum_offset 256
		.amdhsa_reserve_vcc 1
		.amdhsa_float_round_mode_32 0
		.amdhsa_float_round_mode_16_64 0
		.amdhsa_float_denorm_mode_32 3
		.amdhsa_float_denorm_mode_16_64 3
		.amdhsa_dx10_clamp 1
		.amdhsa_ieee_mode 1
		.amdhsa_fp16_overflow 0
		.amdhsa_tg_split 0
		.amdhsa_exception_fp_ieee_invalid_op 0
		.amdhsa_exception_fp_denorm_src 0
		.amdhsa_exception_fp_ieee_div_zero 0
		.amdhsa_exception_fp_ieee_overflow 0
		.amdhsa_exception_fp_ieee_underflow 0
		.amdhsa_exception_fp_ieee_inexact 0
		.amdhsa_exception_int_div_zero 0
	.end_amdhsa_kernel

; #define LAS __attribute__((address_space(3)))
; __global__ void __launch_bounds__(512, 2) mega_fwd(Params p) {
;     extern __shared__ __attribute__((aligned(16))) unsigned char lds_raw[];
;     LAS unsigned char* lds = (LAS unsigned char*)lds_raw;
;     cg::grid_group grid = cg::this_grid();
amdhsa.kernels:
  - .agpr_count:     0
    .args:
      - .offset:         0
        .size:           336
        .value_kind:     by_value
      - .offset:         336
        .size:           4
        .value_kind:     hidden_block_count_x
      - .offset:         340
        .size:           4
        .value_kind:     hidden_block_count_y
      - .offset:         344
        .size:           4
        .value_kind:     hidden_block_count_z
      - .offset:         348
        .size:           2
        .value_kind:     hidden_group_size_x
      - .offset:         350
        .size:           2
        .value_kind:     hidden_group_size_y
      - .offset:         352
        .size:           2
        .value_kind:     hidden_group_size_z
      - .offset:         354
        .size:           2
        .value_kind:     hidden_remainder_x
      - .offset:         356
        .size:           2
        .value_kind:     hidden_remainder_y
      - .offset:         358
        .size:           2
        .value_kind:     hidden_remainder_z
      - .offset:         376
        .size:           8
        .value_kind:     hidden_global_offset_x
      - .offset:         384
        .size:           8
        .value_kind:     hidden_global_offset_y
      - .offset:         392
        .size:           8
        .value_kind:     hidden_global_offset_z
      - .offset:         400
        .size:           2
        .value_kind:     hidden_grid_dims
      - .offset:         424
        .size:           8
        .value_kind:     hidden_multigrid_sync_arg
      - .offset:         456
        .size:           4
        .value_kind:     hidden_dynamic_lds_size
    .group_segment_fixed_size: 0
    .kernarg_segment_align: 8
    .kernarg_segment_size: 592
    .language:       OpenCL C
    .language_version:
      - 2
      - 0
    .max_flat_workgroup_size: 512
    .name:           _Z8mega_fwd6Params
    .private_segment_fixed_size: 0
    .sgpr_count:     108
    .sgpr_spill_count: 130
    .symbol:         _Z8mega_fwd6Params.kd
    .uniform_work_group_size: 1
    .uses_dynamic_stack: false
    .vgpr_count:     256
    .vgpr_spill_count: 0
    .wavefront_size: 64
